# speedup vs baseline: 1.0070x; 1.0070x over previous
; __device__ __forceinline__ void p0_prologue(const Args& a, LAS unsigned char* lds, int tid, int lane, int wave) {
;     ...
;     {
;         f32x4 v[4], nv[4];
; #pragma unroll
;         for (int j = 0; j < 4; ++j) v[j] = (f32x4){0.f, 0.f, 0.f, 0.f};
;         if (gw < MTOT) { const float* xr = (gw < NPROMPT) ? a.in[0] + (size_t)gw * DM : a.in[1] + (size_t)(gw - NPROMPT) * DM;
; #pragma unroll
;             for (int j = 0; j < 4; ++j) v[j] = ((const f32x4*)xr + lane)[64 * j]; }
;         for (int m = gw; m < MTOT; m += NGW) {
;             const int mn = m + NGW;
; #pragma unroll
;             for (int j = 0; j < 4; ++j) nv[j] = v[j];
;             if (mn < MTOT) { const float* xr = (mn < NPROMPT) ? a.in[0] + (size_t)mn * DM : a.in[1] + (size_t)(mn - NPROMPT) * DM;
; #pragma unroll
;                 for (int j = 0; j < 4; ++j) nv[j] = ((const f32x4*)xr + lane)[64 * j]; }
.LBB0_78:
	s_or_b64 exec, exec, s[6:7]
	s_cmp_lt_i32 s20, 0x10800
	s_cbranch_scc0 .LBB0_85
	s_load_dwordx4 s[8:11], s[24:25], 0x0
	s_add_i32 s1, s20, 0xffff0000
	s_ashr_i32 s21, s20, 31
	s_cmp_lt_i32 s20, 0x10000
	s_cselect_b32 s5, s21, 0
	s_cselect_b32 s4, s20, s1
	s_waitcnt lgkmcnt(0)
	s_cselect_b32 s1, s9, s11
	s_cselect_b32 s3, s8, s10
	s_lshl_b64 s[4:5], s[4:5], 12
	s_add_u32 s4, s3, s4
	s_addc_u32 s5, s1, s5
	v_lshlrev_b32_e32 v1, 4, v18
	global_load_dwordx4 v[14:17], v1, s[4:5]
	global_load_dwordx4 v[10:13], v1, s[4:5] offset:1024
	global_load_dwordx4 v[6:9], v1, s[4:5] offset:2048
	global_load_dwordx4 v[2:5], v1, s[4:5] offset:3072
	v_mbcnt_lo_u32_b32 v19, -1, 0
	v_mbcnt_hi_u32_b32 v19, -1, v19
	v_and_b32_e32 v20, 64, v19
	v_add_u32_e32 v20, 64, v20
	v_xor_b32_e32 v21, 1, v19
	v_cmp_lt_i32_e32 vcc, v21, v20
	s_lshl_b64 s[6:7], s[20:21], 2
	s_add_u32 s1, s6, 0x100000
	v_cndmask_b32_e32 v21, v19, v21, vcc
	v_lshlrev_b32_e32 v36, 2, v21
	v_xor_b32_e32 v21, 2, v19
	v_cmp_lt_i32_e32 vcc, v21, v20
	s_addc_u32 s3, s7, 0
	s_ashr_i32 s23, s22, 31
	v_cndmask_b32_e32 v21, v19, v21, vcc
	v_lshlrev_b32_e32 v37, 2, v21
	v_xor_b32_e32 v21, 4, v19
	v_cmp_lt_i32_e32 vcc, v21, v20
	s_lshl_b64 s[24:25], s[20:21], 11
	v_mov_b32_e32 v1, 0
	v_cndmask_b32_e32 v21, v19, v21, vcc
	v_lshlrev_b32_e32 v38, 2, v21
	v_xor_b32_e32 v21, 8, v19
	v_cmp_lt_i32_e32 vcc, v21, v20
	v_cmp_eq_u32_e64 s[4:5], 0, v18
	s_lshl_b64 s[6:7], s[22:23], 2
	v_cndmask_b32_e32 v21, v19, v21, vcc
	v_lshlrev_b32_e32 v39, 2, v21
	v_xor_b32_e32 v21, 16, v19
	v_cmp_lt_i32_e32 vcc, v21, v20
	v_lshl_or_b32 v34, v18, 3, s24
	v_mov_b32_e32 v35, s25
	v_cndmask_b32_e32 v21, v19, v21, vcc
	v_lshlrev_b32_e32 v40, 2, v21
	v_xor_b32_e32 v21, 32, v19
	v_cmp_lt_i32_e32 vcc, v21, v20
	s_lshl_b64 s[24:25], s[22:23], 11
	v_lshlrev_b32_e32 v42, 4, v18
	v_cndmask_b32_e32 v19, v19, v21, vcc
	v_lshlrev_b32_e32 v41, 2, v19
	s_mov_b32 s18, 0x5000000
	s_waitcnt vmcnt(0)
	s_branch .LBB0_81

; __device__ __forceinline__ void p0_prologue(const Args& a, LAS unsigned char* lds, int tid, int lane, int wave) {
;     ...
;         for (int m = gw; m < MTOT; m += NGW) {
;             const int mn = m + NGW;
; #pragma unroll
;             for (int j = 0; j < 4; ++j) nv[j] = v[j];
;             if (mn < MTOT) { const float* xr = (mn < NPROMPT) ? a.in[0] + (size_t)mn * DM : a.in[1] + (size_t)(mn - NPROMPT) * DM;
; #pragma unroll
;                 for (int j = 0; j < 4; ++j) nv[j] = ((const f32x4*)xr + lane)[64 * j]; }
.LBB0_81:
	s_add_i32 s20, s20, s22
	s_cmp_gt_i32 s20, 0x107ff
	s_cselect_b64 s[26:27], -1, 0
	s_and_b64 vcc, exec, s[26:27]
	v_mov_b32_e32 v18, v14
	v_mov_b32_e32 v19, v15
	v_mov_b32_e32 v20, v16
	v_mov_b32_e32 v21, v17
	v_mov_b32_e32 v22, v10
	v_mov_b32_e32 v23, v11
	v_mov_b32_e32 v24, v12
	v_mov_b32_e32 v25, v13
	v_mov_b32_e32 v26, v6
	v_mov_b32_e32 v27, v7
	v_mov_b32_e32 v28, v8
	v_mov_b32_e32 v29, v9
	v_mov_b32_e32 v30, v2
	v_mov_b32_e32 v31, v3
	v_mov_b32_e32 v32, v4
	v_mov_b32_e32 v33, v5
	s_cbranch_vccnz .LBB0_83
	s_add_i32 s21, s20, 0xffff0000
	s_ashr_i32 s23, s20, 31
	s_cmp_lt_i32 s20, 0x10000
	s_cselect_b32 s29, s23, 0
	s_cselect_b32 s28, s20, s21
	s_cselect_b32 s21, s9, s11
	s_cselect_b32 s23, s8, s10
	s_lshl_b64 s[28:29], s[28:29], 12
	s_add_u32 s28, s23, s28
	s_addc_u32 s29, s21, s29
	global_load_dwordx4 v[18:21], v42, s[28:29]
	global_load_dwordx4 v[22:25], v42, s[28:29] offset:1024
	global_load_dwordx4 v[26:29], v42, s[28:29] offset:2048
	global_load_dwordx4 v[30:33], v42, s[28:29] offset:3072

; #define LAS __attribute__((address_space(3)))
; __device__ __forceinline__ void mixer_phase(const Args& a, LAS unsigned char* lds, int l, int pass, int tid, int lane, int wave) {
;     ...
;     LAS float* CST = (LAS float*)(lds + L_CONST);
;     { const int i0 = tid * 8; const float* src = (i0 < 3072) ? conv_w + i0 : gconv + (i0 - 3072);
;       *(LAS pg8::f32x4*)(CST + i0) = *(const pg8::f32x4*)src; *(LAS pg8::f32x4*)(CST + i0 + 4) = *(const pg8::f32x4*)(src + 4);
;       CST[4096 + 2 * tid] = gsgu[2 * tid]; CST[4096 + 2 * tid + 1] = gsgu[2 * tid + 1]; }
;     if (pass == 0 && blockIdx.x == 0) { for (int i = tid; i < NSAMPLE; i += 512) RSB[NPROMPT + i] = 0.f; }
;     __syncthreads();
;     const int ub = (gridDim.x == 256) ? ((int)(blockIdx.x & 7) * 32 + (int)(blockIdx.x >> 3)) : (int)blockIdx.x;
;     for (int unit = ub; unit < nunits; unit += gridDim.x) {
;         const bf16* Pu = PROJ + (size_t)(unit * 128) * PCOLS; const int grow0 = prow0 + unit * 128;
;         {
;             int tl = tid; asm volatile("" : "+v"(tl)); const int lane = tl & 63;
;             const int q = tl >> 4, o = tl & 15, wt = w >> 1, wc2 = w & 1, fr = lane & 15, fq = lane >> 4;
;             constexpr size_t HSTR = (size_t)32768 * 384;
;             const bf16* Hu = PROJ + (size_t)(unit * 128) * 384;
.LBB0_171:
	s_or_b64 exec, exec, s[20:21]
	s_ashr_i32 s46, s28, 6
	s_mul_i32 s100, s0, 0x1800
	s_add_u32 s47, s54, 0x1dc00000
	s_addc_u32 s76, s55, 0
	s_add_u32 s64, s54, 0xd400000
	s_addc_u32 s65, s55, 0
	s_add_u32 s8, s8, s26
	s_addc_u32 s9, s9, s27
	s_add_u32 s10, s10, s26
	s_addc_u32 s11, s11, s27
	v_lshlrev_b32_e32 v212, 4, v122
	v_and_b32_e32 v214, 0xfff, v212
	v_mov_b32_e32 v215, 0
	v_cmp_gt_u32_e32 vcc, 0x1000, v212
	v_mov_b32_e32 v216, s8
	v_mov_b32_e32 v217, s9
	v_mov_b32_e32 v218, s10
	v_mov_b32_e32 v219, s11
	v_cndmask_b32_e32 v216, v218, v216, vcc
	v_cndmask_b32_e32 v217, v219, v217, vcc
	v_lshl_add_u64 v[216:217], v[216:217], 0, v[214:215]
	global_load_dwordx4 v[220:223], v[216:217], off
	v_add_u32_e32 v212, 0x15800, v212
	s_waitcnt vmcnt(0)
	ds_write_b128 v212, v[220:223]
	s_mul_i32 s20, s58, 0x84000
	s_mul_hi_i32 s17, s58, 0x84000
	s_add_u32 s20, s54, s20
	s_addc_u32 s17, s55, s17
	s_mul_hi_i32 s5, s58, 0x10800
	s_mul_i32 s4, s58, 0x10800
	s_add_u32 s66, s20, 0x3b800000
	s_addc_u32 s67, s17, 0
	s_lshl_b64 s[20:21], s[4:5], 2
	s_add_u32 s4, s54, s20
	s_addc_u32 s5, s55, s21
	s_waitcnt lgkmcnt(0)
	s_barrier
	s_load_dword s77, s[92:93], 0x0
	s_add_u32 s68, s4, 0x100000
	s_addc_u32 s69, s5, 0
	s_add_u32 s70, s6, s26
	s_addc_u32 s71, s7, s27
	s_waitcnt lgkmcnt(0)
	s_cmpk_eq_i32 s77, 0x100
	s_cselect_b32 s17, s89, s2
	s_cmpk_gt_i32 s17, 0xff
	s_cbranch_scc1 .LBB0_188
	s_lshl_b32 s4, s58, 4
	s_lshl_b32 s30, s46, 4
	s_bfe_u32 s42, s28, 0x10006
	s_ashr_i32 s5, s4, 31
	s_andn2_b32 s30, s30, 31
	s_lshl_b64 s[6:7], s[4:5], 7
	s_lshl_b32 s35, s42, 6
	s_lshl_b32 s4, s30, 2
	v_readlane_b32 s26, v255, 19
	s_add_i32 s50, s26, s4
	s_lshl_b32 s4, s42, 9
	s_or_b32 s52, s35, 32
	s_or_b32 s59, s35, 48
	s_ashr_i32 s27, s30, 31
	s_add_i32 s50, s50, s4
	s_lshl_b32 s51, s42, 1
	s_lshr_b32 s53, s52, 5
	s_lshr_b32 s72, s59, 5
	s_lshl_b32 s73, s17, 7
	s_lshl_b32 s74, s77, 7
	v_lshl_add_u32 v123, v122, 2, s26
	s_add_u32 s26, s6, s30
	s_addc_u32 s27, s7, s27
	s_add_i32 s6, s0, s73
	s_add_i32 s75, s6, s30
	s_lshl_b32 s6, s42, 8
	s_movk_i32 s4, 0x80
	s_add_i32 s78, s6, 0
	v_cmp_gt_i32_e64 s[4:5], s4, v122
	s_add_i32 s78, s78, 0x14800
	s_branch .LBB0_174

; __device__ __forceinline__ float row_rs(const float* RSS, int grow) { return __builtin_amdgcn_rsqf(RSS[grow] * (1.0f / 1024.0f) + EPS); }
; __device__ __forceinline__ f32x2 vstat(const float* VS, const float* RSS, int grow) { const float rs = row_rs(RSS, grow); const float mean = VS[2 * grow] * (1.0f / 1024.0f); const float var = fmaxf(VS[2 * grow + 1] * (1.0f / 1024.0f) - mean * mean, 0.f); return (f32x2){mean, rs * __builtin_amdgcn_rsqf(rs * rs * var + EPS)}; }
; __device__ __forceinline__ void mixer_phase(const Args& a, LAS unsigned char* lds, int l, int pass, int tid, int lane, int wave) {
;     ...
;             int tl = tid; asm volatile("" : "+v"(tl)); const int lane = tl & 63;
;             const int q = tl >> 4, o = tl & 15, wt = w >> 1, wc2 = w & 1, fr = lane & 15, fq = lane >> 4;
;             constexpr size_t HSTR = (size_t)32768 * 384;
;             const bf16* Hu = PROJ + (size_t)(unit * 128) * 384;
;             const bf16* vsrc = Hu + (size_t)(4 * q) * 384 + 128 + 8 * o;
;             f32x2 st[4];
; #pragma unroll
;             for (int i = 0; i < 4; ++i) st[i] = vstat(VS, RSS, grow0 + 4 * q + i);
;             float ssb[2] = {0.f, 0.f};
;             v4u vr[4];
; #pragma unroll
;             for (int i = 0; i < 4; ++i) vr[i] = *(const v4u*)(vsrc + (size_t)i * 384);
;             const bf16* wm0 = WM + ((size_t)(l * 8 * 2) * 128 + 32 * wt + fr) * 128 + 8 * fq;
;             const int t0 = 32 * wt + fr, cbw = 64 * wc2 + 8 * fq;
;             const float rsr[2] = {row_rs(RSS, grow0 + t0), row_rs(RSS, grow0 + t0 + 16)};
;             UZ uz[2];
; #pragma unroll
;             for (int m = 0; m < 2; ++m) uz[m] = load_uz_hm(Hu + (size_t)(t0 + 16 * m) * 384, sgb + t0 + 16 * m, cbw);
.LBB0_174:
	v_mov_b32_e32 v48, v122
	s_lshl_b32 s6, s17, 7
	s_add_i32 s79, s6, s0
	v_ashrrev_i32_e32 v49, 4, v48
	v_lshlrev_b32_e32 v50, 2, v49
	v_add_u32_e32 v2, s79, v50
	v_ashrrev_i32_e32 v3, 31, v2
	v_lshl_add_u64 v[4:5], v[2:3], 2, s[68:69]
	v_lshlrev_b32_e32 v2, 1, v2
	global_load_dwordx4 v[18:21], v[4:5], off
	v_ashrrev_i32_e32 v3, 31, v2
	v_lshl_add_u64 v[4:5], v[2:3], 2, s[66:67]
	global_load_dwordx3 v[22:24], v[4:5], off
	v_or_b32_e32 v4, 2, v2
	v_or_b32_e32 v6, 4, v2
	v_or_b32_e32 v2, 6, v2
	v_ashrrev_i32_e32 v7, 31, v6
	v_ashrrev_i32_e32 v3, 31, v2
	v_ashrrev_i32_e32 v5, 31, v4
	v_lshl_add_u64 v[6:7], v[6:7], 2, s[66:67]
	v_lshl_add_u64 v[2:3], v[2:3], 2, s[66:67]
	global_load_dwordx2 v[26:27], v[6:7], off
	global_load_dwordx2 v[28:29], v[2:3], off
	v_lshl_add_u64 v[2:3], v[4:5], 2, s[66:67]
	global_load_dword v25, v[2:3], off offset:4
	v_and_b32_e32 v120, 15, v48
	v_lshlrev_b32_e32 v229, 5, v120
	v_add_u32_e32 v229, 0x15800, v229
	v_or_b32_e32 v42, s30, v120
	v_add_u32_e32 v2, s79, v42
	v_ashrrev_i32_e32 v3, 31, v2
	v_lshl_add_u64 v[2:3], v[2:3], 2, s[68:69]
	global_load_dword v34, v[2:3], off
	global_load_dword v35, v[2:3], off offset:64
	s_mul_i32 s7, s17, 0x18000
	s_mul_hi_i32 s44, s6, 0x300
	s_add_u32 s6, s47, s7
	v_bfe_u32 v166, v48, 4, 2
	s_addc_u32 s7, s76, s44
	s_add_u32 s6, s6, s100
	s_addc_u32 s7, s7, 0
	v_ashrrev_i32_e32 v43, 31, v42
	v_lshlrev_b32_e32 v52, 4, v166
	v_mov_b64_e32 v[30:31], s[6:7]
	v_lshl_add_u64 v[128:129], v[42:43], 2, s[70:71]
	v_or_b32_e32 v43, 16, v42
	v_mov_b32_e32 v45, v1
	v_lshlrev_b32_e32 v0, 4, v120
	v_lshl_or_b32 v44, s35, 1, v52
	v_mad_i64_i32 v[2:3], s[6:7], v50, s31, v[30:31]
	v_mad_i64_i32 v[4:5], s[6:7], v42, s31, v[30:31]
	v_lshl_add_u64 v[14:15], v[2:3], 0, v[0:1]
	v_lshl_add_u64 v[32:33], v[4:5], 0, v[44:45]
	global_load_dwordx4 v[2:5], v[14:15], off offset:256
	global_load_dwordx4 v[6:9], v[14:15], off offset:1024
	global_load_dwordx4 v[10:13], v[14:15], off offset:1792
	s_nop 0
	global_load_dwordx4 v[14:17], v[14:15], off offset:2560
	s_nop 0
	global_load_dwordx4 v[74:77], v[32:33], off
	v_lshlrev_b32_e32 v46, 5, v120
	v_mov_b32_e32 v47, v1
	v_lshl_add_u64 v[130:131], s[8:9], 0, v[46:47]
	v_lshl_add_u64 v[132:133], s[10:11], 0, v[46:47]
	v_lshlrev_b32_e32 v46, 2, v48
	v_lshlrev_b32_e32 v51, 3, v48
	v_and_b32_e32 v46, 12, v46
	v_bfe_u32 v47, v48, 2, 2
	v_lshrrev_b32_e32 v53, 1, v49
	v_lshlrev_b32_e32 v49, 3, v49
	v_xor_b32_e32 v47, v47, v53
	v_and_b32_e32 v184, 8, v49
	v_lshl_add_u64 v[134:135], s[64:65], 0, v[44:45]
	s_mul_i32 s43, s73, 0x300
	s_mul_hi_i32 s42, s73, 0x300
	v_mov_b32_e32 v121, v1
	v_mov_b32_e32 v118, 0
	s_mov_b32 s80, 0
	v_mov_b32_e32 v119, v118
	s_waitcnt vmcnt(11)
	v_fmamk_f32 v18, v18, 0x3a800000, v169
	v_rsq_f32_e32 v18, v18
	v_fmamk_f32 v19, v19, 0x3a800000, v169
	s_waitcnt vmcnt(10)
	v_mul_f32_e32 v167, 0x3a800000, v22
	v_rsq_f32_e32 v19, v19
	v_mul_f32_e32 v22, v167, v167
	v_fmamk_f32 v20, v20, 0x3a800000, v169
	v_fmamk_f32 v21, v21, 0x3a800000, v169
	v_mul_f32_e32 v177, 0x3a800000, v24
	v_fma_f32 v22, v23, s23, -v22
	v_rsq_f32_e32 v20, v20
	v_rsq_f32_e32 v21, v21
	v_mul_f32_e32 v24, v177, v177
	s_waitcnt vmcnt(9)
	v_mul_f32_e32 v178, 0x3a800000, v26
	v_max_f32_e32 v22, 0, v22
	v_mul_f32_e32 v26, v18, v18
	s_waitcnt vmcnt(8)
	v_mul_f32_e32 v179, 0x3a800000, v28
	s_waitcnt vmcnt(7)
; __device__ __forceinline__ float row_rs(const float* RSS, int grow) { return __builtin_amdgcn_rsqf(RSS[grow] * (1.0f / 1024.0f) + EPS); }
; __device__ __forceinline__ f32x2 vstat(const float* VS, const float* RSS, int grow) { const float rs = row_rs(RSS, grow); const float mean = VS[2 * grow] * (1.0f / 1024.0f); const float var = fmaxf(VS[2 * grow + 1] * (1.0f / 1024.0f) - mean * mean, 0.f); return (f32x2){mean, rs * __builtin_amdgcn_rsqf(rs * rs * var + EPS)}; }
; __device__ __forceinline__ void mixer_phase(const Args& a, LAS unsigned char* lds, int l, int pass, int tid, int lane, int wave) {
;     ...
;             f32x2 st[4];
; #pragma unroll
;             for (int i = 0; i < 4; ++i) st[i] = vstat(VS, RSS, grow0 + 4 * q + i);
;             float ssb[2] = {0.f, 0.f};
;             v4u vr[4];
; #pragma unroll
;             for (int i = 0; i < 4; ++i) vr[i] = *(const v4u*)(vsrc + (size_t)i * 384);
;             const bf16* wm0 = WM + ((size_t)(l * 8 * 2) * 128 + 32 * wt + fr) * 128 + 8 * fq;
;             const int t0 = 32 * wt + fr, cbw = 64 * wc2 + 8 * fq;
;             const float rsr[2] = {row_rs(RSS, grow0 + t0), row_rs(RSS, grow0 + t0 + 16)};
;             UZ uz[2];
; #pragma unroll
;             for (int m = 0; m < 2; ++m) uz[m] = load_uz_hm(Hu + (size_t)(t0 + 16 * m) * 384, sgb + t0 + 16 * m, cbw);
	v_fma_f32 v23, v25, s23, -v24
	v_mul_f32_e32 v24, v178, v178
	v_fmaak_f32 v22, v26, v22, 0x358637bd
	v_mul_f32_e32 v25, v179, v179
	v_max_f32_e32 v23, 0, v23
	v_fma_f32 v24, v27, s23, -v24
	v_mul_f32_e32 v27, v19, v19
	v_rsq_f32_e32 v22, v22
	v_fma_f32 v25, v29, s23, -v25
	v_fmaak_f32 v23, v27, v23, 0x358637bd
	v_max_f32_e32 v24, 0, v24
	v_mul_f32_e32 v28, v20, v20
	v_max_f32_e32 v25, 0, v25
	v_mul_f32_e32 v29, v21, v21
	v_rsq_f32_e32 v23, v23
	v_fmaak_f32 v24, v28, v24, 0x358637bd
	v_fmaak_f32 v25, v29, v25, 0x358637bd
	v_rsq_f32_e32 v24, v24
	v_rsq_f32_e32 v25, v25
	v_mul_f32_e32 v180, v18, v22
	s_waitcnt vmcnt(6)
	v_fmamk_f32 v18, v34, 0x3a800000, v169
	v_rsq_f32_e32 v124, v18
	s_waitcnt vmcnt(5)
	v_fmamk_f32 v18, v35, 0x3a800000, v169
	v_mul_f32_e32 v181, v19, v23
	v_rsq_f32_e32 v126, v18
	v_mad_i64_i32 v[18:19], s[6:7], v43, s31, v[30:31]
	v_lshl_add_u64 v[22:23], v[18:19], 0, v[44:45]
	v_mul_f32_e32 v182, v20, v24
	v_mul_f32_e32 v183, v21, v25
	global_load_dwordx4 v[82:85], v[32:33], off offset:512
	global_load_dwordx4 v[34:37], v[32:33], off offset:64
	global_load_dwordx4 v[38:41], v[32:33], off offset:576
	s_nop 0
	global_load_dwordx4 v[30:33], v[22:23], off
	global_load_dwordx4 v[26:29], v[22:23], off offset:512
	global_load_dwordx4 v[18:21], v[22:23], off offset:64
	s_nop 0
	global_load_dwordx4 v[22:25], v[22:23], off offset:576
	s_nop 0
	global_load_dword v127, v[128:129], off
	global_load_dword v205, v[128:129], off offset:64
	s_movk_i32 s6, 0x60
	v_and_or_b32 v49, v51, s6, v46
	v_lshlrev_b32_e32 v185, 8, v49
	v_xor_b32_e32 v49, v47, v46
	v_lshlrev_b32_e32 v186, 4, v49
	v_or_b32_e32 v49, 1, v46
	v_xor_b32_e32 v49, v49, v47
	v_lshlrev_b32_e32 v187, 4, v49
	v_or_b32_e32 v49, 2, v46
	v_or_b32_e32 v46, 3, v46
	v_or_b32_e32 v45, s35, v120
	v_xor_b32_e32 v46, v46, v47
	v_lshlrev_b32_e32 v190, 8, v45
	v_bitop3_b32 v45, v48, s51, 15 bitop3:0x6c
	v_lshlrev_b32_e32 v189, 4, v46
	v_xor_b32_e32 v46, v45, v166
	v_lshlrev_b32_e32 v191, 4, v46
	v_or_b32_e32 v46, s52, v120
	v_lshlrev_b32_e32 v192, 8, v46
	v_bitop3_b32 v46, v48, s53, 15 bitop3:0x6c
	v_xor_b32_e32 v49, v49, v47
	v_xor_b32_e32 v47, v46, v166
	v_lshlrev_b32_e32 v193, 4, v47
	v_or_b32_e32 v47, s59, v120
	v_lshlrev_b32_e32 v194, 8, v47
	v_bitop3_b32 v47, v48, s72, 15 bitop3:0x6c
	v_xor_b32_e32 v48, v47, v166
	v_lshlrev_b32_e32 v195, 4, v48
	v_or_b32_e32 v48, 4, v166
	v_lshlrev_b32_e32 v188, 4, v49
	v_xor_b32_e32 v49, v45, v48
	v_lshlrev_b32_e32 v196, 4, v49
	v_xor_b32_e32 v49, v46, v48
	v_xor_b32_e32 v48, v47, v48
	v_lshlrev_b32_e32 v198, 4, v48
	v_or_b32_e32 v48, 8, v166
	v_lshlrev_b32_e32 v197, 4, v49
	v_xor_b32_e32 v49, v45, v48
	v_lshlrev_b32_e32 v199, 4, v49
	v_xor_b32_e32 v49, v46, v48
	v_xor_b32_e32 v48, v47, v48
	v_lshlrev_b32_e32 v201, 4, v48
	v_or_b32_e32 v48, 12, v166
	v_xor_b32_e32 v45, v45, v48
	s_add_u32 s6, s43, 0x1f400700
	v_lshlrev_b32_e32 v202, 4, v45
	v_xor_b32_e32 v45, v46, v48
	s_addc_u32 s7, s42, 0
	s_add_u32 s6, s6, s100
	s_addc_u32 s7, s7, 0
	v_lshlrev_b32_e32 v203, 4, v45
	v_xor_b32_e32 v45, v47, v48
	v_mov_b64_e32 v[46:47], s[6:7]
	v_mad_i64_i32 v[136:137], s[6:7], v50, s31, v[46:47]
	v_lshl_add_u64 v[46:47], s[26:27], 0, v[120:121]
	v_lshlrev_b64 v[138:139], 8, v[46:47]
	v_add_u32_e32 v46, s75, v120
	s_add_u32 s6, s43, 0x1f400200
	v_ashrrev_i32_e32 v47, 31, v46
	s_addc_u32 s7, s42, 0
	s_add_u32 s6, s6, s100
	s_addc_u32 s7, s7, 0
	v_lshlrev_b64 v[140:141], 8, v[46:47]
	v_mov_b64_e32 v[46:47], s[6:7]
	v_mad_i64_i32 v[144:145], s[6:7], v42, s31, v[46:47]
	v_mad_i64_i32 v[146:147], s[6:7], v43, s31, v[46:47]
	v_lshlrev_b32_e32 v200, 4, v49
	v_lshlrev_b32_e32 v204, 4, v45
	v_or_b32_e32 v136, v136, v0
	v_or_b32_e32 v138, v138, v52
	v_or_b32_e32 v142, v140, v44
	v_mov_b32_e32 v143, v141
	v_or_b32_e32 v144, v144, v44
	v_or_b32_e32 v146, v146, v44
	v_lshl_add_u32 v0, v166, 5, s78
	s_mov_b64 s[42:43], 0
	s_branch .LBB0_176

; #define LAS __attribute__((address_space(3)))
; __device__ __forceinline__ unsigned pk2(float lo, float hi) { unsigned r; asm("v_cvt_pk_bf16_f32 %0, %1, %2" : "=v"(r) : "v"(lo), "v"(hi)); return r; }
; __device__ __forceinline__ void vt_write(LAS unsigned char* VT, const v4u (&vr)[4], const f32x2 (&st)[4], const float* lng8, const float* lnb8, int q, int o) {
;     float lg8[8], lb8[8]; { const f32x4 g0 = *(const f32x4*)lng8, g1 = *(const f32x4*)(lng8 + 4), b0 = *(const f32x4*)lnb8, b1 = *(const f32x4*)(lnb8 + 4);
; #pragma unroll
;         for (int e = 0; e < 4; ++e) { lg8[e] = g0[e]; lg8[4 + e] = g1[e]; lb8[e] = b0[e]; lb8[4 + e] = b1[e]; } }
;     float x[4][8];
; #pragma unroll
;     for (int i = 0; i < 4; ++i) { unpack8s(vr[i], x[i]);
; #pragma unroll
;         for (int j = 0; j < 8; ++j) x[i][j] = (x[i][j] - st[i].x) * st[i].y * lg8[j] + lb8[j]; }
; #pragma unroll
;     for (int j = 0; j < 8; ++j) { const int R = 32 * (o >> 2) + 16 * (j >> 2) + 4 * (o & 3) + (j & 3); const int f = (R & 15) ^ ((R >> 5) & 3);
;         const unsigned lo = pk2(x[0][j], x[1][j]), hi = pk2(x[2][j], x[3][j]);
;         *(LAS unsigned long long*)(VT + R * 256 + (((q >> 1) ^ f) << 4) + 8 * (q & 1)) = (unsigned long long)lo | ((unsigned long long)hi << 32); }
; __device__ __forceinline__ void mixer_phase(const Args& a, LAS unsigned char* lds, int l, int pass, int tid, int lane, int wave) {
;     ...
;             for (int g = 0; g < 8; ++g) {
;                 LAS unsigned char* VT = lds + ((g & 1) ? L_VT1 : L_VT0);
;                 bf16x8 Af[2][4];
; #pragma unroll
;                 for (int m = 0; m < 2; ++m)
; #pragma unroll
;                     for (int k = 0; k < 4; ++k) Af[m][k] = *(const bf16x8*)(wm0 + (size_t)g * 2 * 16384 + (size_t)m * 16 * 128 + 32 * k);
;                 vt_write(VT, vr, st, lng + 128 * g + 8 * o, lnb + 128 * g + 8 * o, q, o);
;                 if (g < 7) {
; #pragma unroll
;                     for (int i = 0; i < 4; ++i) vr[i] = *(const v4u*)(vsrc + (size_t)(g + 1) * HSTR + (size_t)i * 384); }
.LBB0_176:
	v_add_u32_e32 v44, s42, v229
	ds_read_b128 v[78:81], v44 offset:4096
	ds_read_b128 v[86:89], v44
	ds_read_b128 v[90:93], v44 offset:16
	ds_read_b128 v[94:97], v44 offset:4112
	v_lshl_add_u64 v[42:43], s[54:55], 0, v[138:139]
	v_add_co_u32_e32 v44, vcc, s25, v42
	s_mov_b32 s7, 0x401000
	s_nop 0
	v_addc_co_u32_e32 v45, vcc, 0, v43, vcc
	v_add_co_u32_e32 v58, vcc, s7, v42
	s_waitcnt vmcnt(13)
	v_lshlrev_b32_e32 v46, 16, v2
	v_and_b32_e32 v47, 0xffff0000, v2
	v_lshlrev_b32_e32 v48, 16, v3
	v_and_b32_e32 v49, 0xffff0000, v3
	v_lshlrev_b32_e32 v50, 16, v4
	v_and_b32_e32 v51, 0xffff0000, v4
	v_lshlrev_b32_e32 v52, 16, v5
	v_and_b32_e32 v53, 0xffff0000, v5
	s_waitcnt vmcnt(12)
	v_lshlrev_b32_e32 v54, 16, v6
	v_and_b32_e32 v55, 0xffff0000, v6
	v_lshlrev_b32_e32 v56, 16, v7
	v_and_b32_e32 v57, 0xffff0000, v7
	v_lshlrev_b32_e32 v60, 16, v8
	v_and_b32_e32 v61, 0xffff0000, v8
	v_addc_co_u32_e32 v59, vcc, 0, v43, vcc
	v_sub_f32_e32 v100, v46, v167
	v_sub_f32_e32 v101, v47, v167
	v_sub_f32_e32 v102, v48, v167
	v_sub_f32_e32 v103, v49, v167
	v_sub_f32_e32 v104, v50, v167
	v_sub_f32_e32 v105, v51, v167
	v_sub_f32_e32 v106, v52, v167
	v_sub_f32_e32 v107, v53, v167
	v_sub_f32_e32 v108, v54, v177
	v_sub_f32_e32 v109, v55, v177
	v_sub_f32_e32 v110, v56, v177
	v_sub_f32_e32 v111, v57, v177
	v_sub_f32_e32 v112, v60, v177
	v_sub_f32_e32 v113, v61, v177
	global_load_dwordx4 v[62:65], v[44:45], off offset:64
	global_load_dwordx4 v[50:53], v[44:45], off offset:128
	s_nop 0
	global_load_dwordx4 v[42:45], v[44:45], off offset:192
	s_nop 0
	global_load_dwordx4 v[70:73], v[58:59], off offset:-4096
	global_load_dwordx4 v[66:69], v[58:59], off
	global_load_dwordx4 v[54:57], v[58:59], off offset:64
	global_load_dwordx4 v[46:49], v[58:59], off offset:128
	s_nop 0
	global_load_dwordx4 v[58:61], v[58:59], off offset:192
	s_waitcnt vmcnt(19)
	v_lshlrev_b32_e32 v114, 16, v10
	s_waitcnt vmcnt(18)
	v_lshlrev_b32_e32 v150, 16, v14
	v_sub_f32_e32 v114, v114, v178
	v_sub_f32_e32 v150, v150, v179
	v_mul_f32_e32 v100, v180, v100
	v_mul_f32_e32 v108, v181, v108
	v_and_b32_e32 v115, 0xffff0000, v10
	v_mul_f32_e32 v114, v182, v114
	v_and_b32_e32 v151, 0xffff0000, v14
	v_mul_f32_e32 v150, v183, v150
	v_sub_f32_e32 v115, v115, v178
	v_mul_f32_e32 v101, v180, v101
	v_mul_f32_e32 v109, v181, v109
	v_lshlrev_b32_e32 v116, 16, v11
	v_mul_f32_e32 v115, v182, v115
	v_lshlrev_b32_e32 v154, 16, v15
	v_sub_f32_e32 v116, v116, v178
	v_mul_f32_e32 v102, v180, v102
	v_mul_f32_e32 v110, v181, v110
	v_and_b32_e32 v117, 0xffff0000, v11
	v_mul_f32_e32 v116, v182, v116
	v_and_b32_e32 v155, 0xffff0000, v15
	v_sub_f32_e32 v117, v117, v178
	v_mul_f32_e32 v103, v180, v103
	v_mul_f32_e32 v111, v181, v111
	v_mul_f32_e32 v117, v182, v117
	v_lshlrev_b32_e32 v156, 16, v16
	v_and_b32_e32 v157, 0xffff0000, v16
	v_lshlrev_b32_e32 v121, 16, v12
	v_lshlrev_b32_e32 v158, 16, v17
	v_sub_f32_e32 v121, v121, v178
	s_and_b32 s6, s80, 0x8000
	v_and_b32_e32 v99, 0xffff0000, v9
	v_mul_f32_e32 v104, v180, v104
	v_mul_f32_e32 v112, v181, v112
	v_and_b32_e32 v125, 0xffff0000, v12
	v_and_b32_e32 v149, 0xffff0000, v13
	v_mul_f32_e32 v121, v182, v121
	s_waitcnt lgkmcnt(0)
	v_fma_f32 v100, v100, v86, v78
	v_fma_f32 v108, v108, v86, v78
	v_fma_f32 v114, v114, v86, v78
	v_fma_f32 v86, v150, v86, v78
	v_sub_f32_e32 v78, v151, v179
	v_mul_f32_e32 v78, v183, v78
	v_fma_f32 v101, v101, v87, v79
	v_fma_f32 v109, v109, v87, v79
	v_fma_f32 v115, v115, v87, v79
	v_fma_f32 v87, v78, v87, v79
	v_sub_f32_e32 v78, v154, v179
	v_mul_f32_e32 v78, v183, v78
	v_fma_f32 v102, v102, v88, v80
	v_fma_f32 v110, v110, v88, v80
	v_fma_f32 v116, v116, v88, v80
	v_fma_f32 v80, v78, v88, v80
	v_sub_f32_e32 v78, v155, v179
	v_mul_f32_e32 v78, v183, v78
	v_fma_f32 v103, v103, v89, v81
	v_fma_f32 v111, v111, v89, v81
	v_fma_f32 v117, v117, v89, v81
	v_fmac_f32_e32 v81, v78, v89
	v_sub_f32_e32 v78, v156, v179
	v_mul_f32_e32 v78, v183, v78
	v_fma_f32 v88, v78, v90, v94
	v_sub_f32_e32 v78, v157, v179
	v_mul_f32_e32 v78, v183, v78
	v_fma_f32 v89, v78, v91, v95
	v_sub_f32_e32 v78, v158, v179
	v_and_b32_e32 v159, 0xffff0000, v17
	v_mul_f32_e32 v78, v183, v78
	s_add_i32 s6, s6, 0
	v_fma_f32 v104, v104, v90, v94
	v_fma_f32 v112, v112, v90, v94
	v_sub_f32_e32 v99, v99, v177
	v_fma_f32 v121, v121, v90, v94
	v_sub_f32_e32 v125, v125, v178
	v_sub_f32_e32 v149, v149, v178
	v_fma_f32 v90, v78, v92, v96
	v_sub_f32_e32 v78, v159, v179
	v_mul_f32_e32 v105, v180, v105
	v_mul_f32_e32 v107, v180, v107
	v_mul_f32_e32 v113, v181, v113
	v_mul_f32_e32 v99, v181, v99
	v_mul_f32_e32 v125, v182, v125
	v_mul_f32_e32 v149, v182, v149
	v_mul_f32_e32 v78, v183, v78
	v_cvt_pk_bf16_f32 v79, v114, v86
	v_add_u32_e32 v86, s6, v185
	v_fma_f32 v105, v105, v91, v95
	v_fma_f32 v107, v107, v93, v97
	v_fma_f32 v113, v113, v91, v95
	v_fma_f32 v99, v99, v93, v97
	v_fma_f32 v125, v125, v91, v95
	v_fma_f32 v149, v149, v93, v97
	v_fmac_f32_e32 v97, v78, v93
	v_cvt_pk_bf16_f32 v78, v100, v108
	v_add3_u32 v91, v86, v186, v184
	ds_write_b64 v91, v[78:79]
	v_cvt_pk_bf16_f32 v78, v101, v109
	v_cvt_pk_bf16_f32 v79, v115, v87
	v_add3_u32 v87, v86, v187, v184
	ds_write_b64 v87, v[78:79] offset:256
	v_cvt_pk_bf16_f32 v78, v102, v110
	v_cvt_pk_bf16_f32 v79, v116, v80
	v_add3_u32 v80, v86, v188, v184
	v_lshlrev_b32_e32 v98, 16, v9
	v_lshlrev_b32_e32 v148, 16, v13
	ds_write_b64 v80, v[78:79] offset:512
	v_cvt_pk_bf16_f32 v78, v103, v111
	v_cvt_pk_bf16_f32 v79, v117, v81
	v_add3_u32 v81, v86, v189, v184
	v_sub_f32_e32 v98, v98, v177
	v_sub_f32_e32 v148, v148, v178
	ds_write_b64 v81, v[78:79] offset:768
	v_cvt_pk_bf16_f32 v78, v104, v112
	v_cvt_pk_bf16_f32 v79, v121, v88
	v_mul_f32_e32 v106, v180, v106
	v_mul_f32_e32 v98, v181, v98
	v_mul_f32_e32 v148, v182, v148
	ds_write_b64 v91, v[78:79] offset:4096
	v_cvt_pk_bf16_f32 v78, v105, v113
	v_cvt_pk_bf16_f32 v79, v125, v89
	s_cmpk_lg_i32 s42, 0xe00
	v_fma_f32 v106, v106, v92, v96
	v_fma_f32 v98, v98, v92, v96
	v_fma_f32 v148, v148, v92, v96
	ds_write_b64 v87, v[78:79] offset:4352
	v_cvt_pk_bf16_f32 v78, v106, v98
	v_cvt_pk_bf16_f32 v79, v148, v90
	s_cselect_b64 s[44:45], -1, 0
	s_cmpk_eq_i32 s42, 0xe00
	ds_write_b64 v80, v[78:79] offset:4608
	v_cvt_pk_bf16_f32 v78, v107, v99
	v_cvt_pk_bf16_f32 v79, v149, v97
	ds_write_b64 v81, v[78:79] offset:4864
	v_lshl_add_u64 v[14:15], s[54:55], 0, v[136:137]
	global_load_dwordx4 v[2:5], v[14:15], off offset:-1536
	global_load_dwordx4 v[6:9], v[14:15], off offset:-768
	global_load_dwordx4 v[10:13], v[14:15], off
	s_nop 0
	global_load_dwordx4 v[14:17], v[14:15], off offset:768
; #define LAS __attribute__((address_space(3)))
; __device__ __forceinline__ void mixer_phase(const Args& a, LAS unsigned char* lds, int l, int pass, int tid, int lane, int wave) {
;     ...
;                 __syncthreads();
;                 pg8::f32x4 acc[2][4];
; #pragma unroll
;                 for (int m = 0; m < 2; ++m)
; #pragma unroll
;                     for (int n = 0; n < 4; ++n) acc[m][n] = (pg8::f32x4){0.f, 0.f, 0.f, 0.f};
; #pragma unroll
;                 for (int k = 0; k < 4; ++k) {
;                     bf16x8 Bf[4];
; #pragma unroll
;                     for (int n = 0; n < 4; ++n) { const int R = 64 * wc2 + 16 * n + fr; const int f = (R & 15) ^ ((R >> 5) & 3); Bf[n] = *(const LAS bf16x8*)(VT + R * 256 + (((4 * k + fq) ^ f) << 4)); }
; #pragma unroll
;                     for (int m = 0; m < 2; ++m)
; #pragma unroll
;                         for (int n = 0; n < 4; ++n) acc[m][n] = __builtin_amdgcn_mfma_f32_16x16x32_bf16(Bf[n], Af[m][k], acc[m][n], 0, 0, 0);
;                 }
;                 UZ nz[2];
; #pragma unroll
;                 for (int m = 0; m < 2; ++m) { nz[m] = uz[m]; if (g < 7) nz[m] = load_uz_hm(Hu + (size_t)(g + 1) * HSTR + (size_t)(t0 + 16 * m) * 384, sgb + (g + 1) * 128 + t0 + 16 * m, cbw); }
; #pragma unroll
;                 for (int m = 0; m < 2; ++m) ssb[m] += sgu_epi(uz[m], acc[m], YMIX + ((size_t)g * MTOT + grow0 + t0 + 16 * m) * 128, 128 * g + cbw, CST + 4096, rsr[m]);
; #pragma unroll
;                 for (int m = 0; m < 2; ++m) uz[m] = nz[m];
.LBB0_178:
	v_add_u32_e32 v121, s6, v190
	v_add_u32_e32 v125, s6, v192
	v_add_u32_e32 v154, s6, v194
	v_add_u32_e32 v86, v121, v191
	v_add_u32_e32 v94, v125, v193
	v_add_u32_e32 v102, v154, v195
	s_waitcnt lgkmcnt(0)
	s_barrier
	ds_read_b128 v[78:81], v86
	ds_read_b128 v[86:89], v86 offset:4096
	ds_read_b128 v[94:97], v94
	ds_read_b128 v[102:105], v102
	v_add_u32_e32 v114, v121, v196
	s_waitcnt vmcnt(4) lgkmcnt(3)
	v_mfma_f32_16x16x32_bf16 v[90:93], v[78:81], v[70:73], 0
	ds_read_b128 v[110:113], v114
	v_add_u32_e32 v148, v154, v198
	ds_read_b128 v[148:151], v148
	s_waitcnt lgkmcnt(4)
	v_mfma_f32_16x16x32_bf16 v[98:101], v[86:89], v[70:73], 0
	s_andn2_b64 vcc, exec, s[44:45]
	s_waitcnt lgkmcnt(3)
	v_mfma_f32_16x16x32_bf16 v[106:109], v[94:97], v[70:73], 0
	s_waitcnt lgkmcnt(2)
	v_mfma_f32_16x16x32_bf16 v[70:73], v[102:105], v[70:73], 0
	s_waitcnt vmcnt(4)
	v_mfma_f32_16x16x32_bf16 v[78:81], v[78:81], v[66:69], 0
	v_mfma_f32_16x16x32_bf16 v[86:89], v[86:89], v[66:69], 0
	v_mfma_f32_16x16x32_bf16 v[94:97], v[94:97], v[66:69], 0
	v_mfma_f32_16x16x32_bf16 v[66:69], v[102:105], v[66:69], 0
	ds_read_b128 v[102:105], v114 offset:4096
	v_add_u32_e32 v114, v125, v197
	ds_read_b128 v[114:117], v114
	s_waitcnt lgkmcnt(3)
	v_mfma_f32_16x16x32_bf16 v[90:93], v[110:113], v[62:65], v[90:93]
	s_waitcnt lgkmcnt(1)
	v_mfma_f32_16x16x32_bf16 v[98:101], v[102:105], v[62:65], v[98:101]
	s_waitcnt lgkmcnt(0)
	v_mfma_f32_16x16x32_bf16 v[106:109], v[114:117], v[62:65], v[106:109]
	v_mfma_f32_16x16x32_bf16 v[62:65], v[148:151], v[62:65], v[70:73]
	s_waitcnt vmcnt(4)
	v_mfma_f32_16x16x32_bf16 v[70:73], v[110:113], v[54:57], v[78:81]
	v_add_u32_e32 v110, v154, v201
	ds_read_b128 v[110:113], v110
	v_mfma_f32_16x16x32_bf16 v[78:81], v[102:105], v[54:57], v[86:89]
	v_add_u32_e32 v102, v121, v199
	v_mfma_f32_16x16x32_bf16 v[86:89], v[114:117], v[54:57], v[94:97]
	s_nop 2
	ds_read_b128 v[94:97], v102
	v_mfma_f32_16x16x32_bf16 v[54:57], v[148:151], v[54:57], v[66:69]
	s_nop 2
	ds_read_b128 v[66:69], v102 offset:4096
	v_add_u32_e32 v102, v125, v200
	ds_read_b128 v[102:105], v102
	s_waitcnt lgkmcnt(2)
	v_mfma_f32_16x16x32_bf16 v[90:93], v[94:97], v[50:53], v[90:93]
	s_waitcnt lgkmcnt(1)
	v_mfma_f32_16x16x32_bf16 v[98:101], v[66:69], v[50:53], v[98:101]
	s_waitcnt lgkmcnt(0)
	v_mfma_f32_16x16x32_bf16 v[106:109], v[102:105], v[50:53], v[106:109]
	v_mfma_f32_16x16x32_bf16 v[50:53], v[110:113], v[50:53], v[62:65]
	s_waitcnt vmcnt(4)
	v_mfma_f32_16x16x32_bf16 v[62:65], v[94:97], v[46:49], v[70:73]
	v_mfma_f32_16x16x32_bf16 v[70:73], v[102:105], v[46:49], v[86:89]
	v_lshl_add_u64 v[102:103], v[128:129], 0, s[42:43]
	s_nop 1
	v_add_u32_e32 v86, v121, v202
	v_mfma_f32_16x16x32_bf16 v[148:151], v[110:113], v[46:49], v[54:57]
	v_mov_b32_e32 v121, v127
	s_nop 1
	v_add_u32_e32 v54, v125, v203
	v_mfma_f32_16x16x32_bf16 v[66:69], v[66:69], v[46:49], v[78:81]
	ds_read_b128 v[46:49], v86 offset:4096
	ds_read_b128 v[54:57], v54
	s_nop 0
	ds_read_b128 v[78:81], v86
	v_add_u32_e32 v86, v154, v204
	ds_read_b128 v[154:157], v86
	s_waitcnt lgkmcnt(1)
	v_mfma_f32_16x16x32_bf16 v[114:117], v[78:81], v[42:45], v[90:93]
	v_mfma_f32_16x16x32_bf16 v[98:101], v[46:49], v[42:45], v[98:101]
	v_mfma_f32_16x16x32_bf16 v[110:113], v[54:57], v[42:45], v[106:109]
	s_waitcnt lgkmcnt(0)
	v_mfma_f32_16x16x32_bf16 v[106:109], v[154:157], v[42:45], v[50:53]
	v_cndmask_b32_e64 v42, 0, 1, s[44:45]
	v_cmp_ne_u32_e64 s[6:7], 1, v42
	v_mov_b64_e32 v[42:43], v[74:75]
	s_waitcnt vmcnt(4)
	v_mfma_f32_16x16x32_bf16 v[94:97], v[78:81], v[58:61], v[62:65]
	v_mov_b64_e32 v[50:51], v[82:83]
	v_mov_b64_e32 v[44:45], v[76:77]
	v_mov_b64_e32 v[52:53], v[84:85]
	v_mfma_f32_16x16x32_bf16 v[90:93], v[46:49], v[58:61], v[66:69]
	v_mov_b64_e32 v[48:49], v[36:37]
	v_mov_b64_e32 v[46:47], v[34:35]
	v_mfma_f32_16x16x32_bf16 v[86:89], v[54:57], v[58:61], v[70:73]
	v_mov_b64_e32 v[56:57], v[40:41]
	v_mov_b64_e32 v[54:55], v[38:39]
	v_mfma_f32_16x16x32_bf16 v[78:81], v[154:157], v[58:61], v[148:151]
	s_cbranch_vccnz .LBB0_180
	v_lshl_add_u64 v[54:55], s[54:55], 0, v[144:145]
	global_load_dwordx4 v[42:45], v[54:55], off offset:-512
	global_load_dwordx4 v[46:49], v[54:55], off offset:-448
	global_load_dwordx4 v[50:53], v[54:55], off
	s_nop 0
	global_load_dwordx4 v[54:57], v[54:55], off offset:64
	s_nop 0
	global_load_dword v121, v[102:103], off offset:512

;     __device__ __forceinline__ void operator()(const f32x4 (&acc)[2][2][4][2], const Unit& u, int wr, int wc, int fr, int fq, int) const {
;     ...
;                     bf16_t* rowp = hm ? O + ((size_t)hd0 * 32768 + r) * 384 + cin : O + (size_t)r * ldc + col0; const size_t bjs = hm ? (size_t)32768 * 384 : (size_t)HALF; float s1 = 0.f, s2 = 0.f;
.LBB0_252:
	s_lshl_b32 s10, s20, 16
	s_and_b32 s28, s10, 0x30000
	s_lshl_b32 s100, s0, 3
	s_add_i32 s28, s28, s100
	s_lshl_b32 s10, s20, 5
	v_lshl_add_u32 v0, s20, 8, v180
	s_and_b32 s10, s10, 0x7fffff80
	v_add_u32_e32 v136, s10, v181
	v_mov_b32_e32 v137, v1
	s_mov_b64 s[10:11], 0x80
	s_andn2_b64 vcc, exec, s[12:13]
	v_mov_b64_e32 v[132:133], v[0:1]
	s_cbranch_vccnz .LBB0_254
	v_lshl_add_u64 v[132:133], v[134:135], 0, s[28:29]
	v_mad_u64_u32 v[130:131], s[10:11], v132, s31, 0
	v_mad_i32_i24 v131, v133, s31, v131
	s_mov_b64 s[10:11], 0xc00000
	v_mov_b64_e32 v[132:133], v[136:137]

; __device__ __forceinline__ unsigned cvt_pk_bf16(float lo, float hi) { unsigned r; asm volatile("v_cvt_pk_bf16_f32 %0, %1, %2" : "=v"(r) : "v"(lo), "v"(hi)); return r; }
;     __device__ __forceinline__ void operator()(const f32x4 (&acc)[2][2][4][2], const Unit& u, int wr, int wc, int fr, int fq, int ui) const {
;         const int row0 = u.pm * BM + wr * 64 + fr, col0 = u.pn * BM + wc * 32 + 8 * fq;
; #pragma unroll
;         for (int ai = 0; ai < 2; ++ai)
; #pragma unroll
;             for (int m = 0; m < 4; ++m) { const int r = row0 + ai * HALF + m * 16; bf16_t* xp = xb + (size_t)r * 1024 + col0; float ss = 0.f; const float sa = sc[(ui & 1) * 512 + 256 + ai * HALF + wr * 64 + m * 16 + fr];
; #pragma unroll
;                 for (int bj = 0; bj < 2; ++bj) {
;                     const u32x4 b = *(const u32x4*)(xp + bj * HALF);
;                     f32x4 v0 = acc[ai][bj][m][0] * sa, v1 = acc[ai][bj][m][1] * sa;
;                     v0[0] += __builtin_bit_cast(float, b.x << 16); v0[1] += __builtin_bit_cast(float, b.x & 0xffff0000u); v0[2] += __builtin_bit_cast(float, b.y << 16); v0[3] += __builtin_bit_cast(float, b.y & 0xffff0000u);
;                     v1[0] += __builtin_bit_cast(float, b.z << 16); v1[1] += __builtin_bit_cast(float, b.z & 0xffff0000u); v1[2] += __builtin_bit_cast(float, b.w << 16); v1[3] += __builtin_bit_cast(float, b.w & 0xffff0000u);
;                     ss += (v0[0] * v0[0] + v0[1] * v0[1]) + (v0[2] * v0[2] + v0[3] * v0[3]) + (v1[0] * v1[0] + v1[1] * v1[1]) + (v1[2] * v1[2] + v1[3] * v1[3]);
;                     u32x4 w; w.x = cvt_pk_bf16(v0[0], v0[1]); w.y = cvt_pk_bf16(v0[2], v0[3]); w.z = cvt_pk_bf16(v1[0], v1[1]); w.w = cvt_pk_bf16(v1[2], v1[3]);
;                     *(u32x4*)(xp + bj * HALF) = w; }
;                 ss += __shfl_xor(ss, 16); ss += __shfl_xor(ss, 32);
;                 if (fq == 0) unsafeAtomicAdd(rowss + r, ss);
;                 if (m & 1) asm volatile("" ::: "memory"); }
.LBB0_394:
	v_lshl_add_u32 v146, s77, 8, v149
	v_ashrrev_i32_e32 v147, 31, v146
	v_lshl_or_b32 v144, s76, 8, v155
	v_lshlrev_b64 v[2:3], 11, v[146:147]
	v_ashrrev_i32_e32 v145, 31, v144
	v_lshl_add_u64 v[2:3], s[60:61], 0, v[2:3]
	v_lshl_add_u64 v[2:3], v[144:145], 1, v[2:3]
	global_load_dwordx4 v[158:161], v[2:3], off
	global_load_dwordx4 v[162:165], v[2:3], off offset:256
	s_mov_b32 s100, 0x8000
	s_mov_b32 s101, 0
	v_lshl_add_u64 v[234:235], v[2:3], 0, s[100:101]
	global_load_dwordx4 v[178:181], v[234:235], off
	global_load_dwordx4 v[182:185], v[234:235], off offset:256
	v_lshl_add_u64 v[234:235], v[234:235], 0, s[100:101]
	global_load_dwordx4 v[186:189], v[234:235], off
	global_load_dwordx4 v[190:193], v[234:235], off offset:256
	v_lshl_add_u64 v[234:235], v[234:235], 0, s[100:101]
	global_load_dwordx4 v[194:197], v[234:235], off
	global_load_dwordx4 v[198:201], v[234:235], off offset:256
	s_mov_b32 s100, 0x28000
	v_lshl_add_u64 v[234:235], v[234:235], 0, s[100:101]
	global_load_dwordx4 v[202:205], v[234:235], off
	global_load_dwordx4 v[206:209], v[234:235], off offset:256
	s_mov_b32 s100, 0x8000
	v_lshl_add_u64 v[234:235], v[234:235], 0, s[100:101]
	global_load_dwordx4 v[210:213], v[234:235], off
	global_load_dwordx4 v[214:217], v[234:235], off offset:256
	v_lshl_add_u64 v[234:235], v[234:235], 0, s[100:101]
	global_load_dwordx4 v[218:221], v[234:235], off
	global_load_dwordx4 v[222:225], v[234:235], off offset:256
	v_lshl_add_u64 v[234:235], v[234:235], 0, s[100:101]
	global_load_dwordx4 v[226:229], v[234:235], off
	global_load_dwordx4 v[230:233], v[234:235], off offset:256
	s_lshl_b32 s42, s70, 2
	s_add_i32 s27, s27, s42
	v_lshl_add_u32 v157, v148, 2, s27
	ds_read_b32 v0, v157 offset:1024
	s_waitcnt lgkmcnt(0)
	v_pk_mul_f32 v[128:129], v[128:129], v[0:1] op_sel_hi:[1,0]
	v_pk_mul_f32 v[130:131], v[130:131], v[0:1] op_sel_hi:[1,0]
	v_pk_mul_f32 v[124:125], v[124:125], v[0:1] op_sel_hi:[1,0]
	v_pk_mul_f32 v[126:127], v[126:127], v[0:1] op_sel_hi:[1,0]
	v_pk_mul_f32 v[122:123], v[122:123], v[0:1] op_sel_hi:[1,0]
	v_pk_mul_f32 v[120:121], v[120:121], v[0:1] op_sel_hi:[1,0]
	v_pk_mul_f32 v[118:119], v[118:119], v[0:1] op_sel_hi:[1,0]
	v_pk_mul_f32 v[116:117], v[116:117], v[0:1] op_sel_hi:[1,0]
	s_waitcnt vmcnt(15)
	s_nop 1
	v_lshlrev_b32_e32 v150, 16, v158
	v_add_f32_e32 v128, v128, v150
	v_and_b32_e32 v150, 0xffff0000, v158
	v_add_f32_e32 v129, v129, v150
	v_lshlrev_b32_e32 v150, 16, v159
	v_add_f32_e32 v130, v130, v150
	v_and_b32_e32 v150, 0xffff0000, v159
	v_add_f32_e32 v131, v131, v150
	v_lshlrev_b32_e32 v150, 16, v160
	v_add_f32_e32 v150, v124, v150
	v_and_b32_e32 v124, 0xffff0000, v160
	v_add_f32_e32 v151, v125, v124
	v_lshlrev_b32_e32 v124, 16, v161
	v_add_f32_e32 v158, v126, v124
	v_and_b32_e32 v124, 0xffff0000, v161
	v_add_f32_e32 v127, v127, v124
	v_mul_f32_e32 v124, v129, v129
	v_mul_f32_e32 v125, v131, v131
	v_fmac_f32_e32 v124, v128, v128
	v_fmac_f32_e32 v125, v130, v130
	v_add_f32_e32 v124, v124, v125
	v_mul_f32_e32 v125, v151, v151
	v_fmac_f32_e32 v125, v150, v150
	v_add_f32_e32 v124, v125, v124
	v_mul_f32_e32 v125, v127, v127
	v_fmac_f32_e32 v125, v158, v158
	v_add_f32_e32 v159, v125, v124
	v_cvt_pk_bf16_f32 v124, v128, v129
	v_cvt_pk_bf16_f32 v125, v130, v131
	v_cvt_pk_bf16_f32 v126, v150, v151
	v_cvt_pk_bf16_f32 v127, v158, v127
	global_store_dwordx4 v[2:3], v[124:127], off
	s_nop 0
	s_waitcnt vmcnt(15)
	s_nop 1
	v_mov_b64_e32 v[124:125], v[162:163]
	v_mov_b64_e32 v[126:127], v[164:165]
	v_lshlrev_b32_e32 v0, 16, v124
	v_add_f32_e32 v0, v120, v0
	v_and_b32_e32 v120, 0xffff0000, v124
	v_add_f32_e32 v120, v121, v120
	v_lshlrev_b32_e32 v121, 16, v125
	v_add_f32_e32 v121, v122, v121
	v_and_b32_e32 v122, 0xffff0000, v125
	v_add_f32_e32 v122, v123, v122
	v_lshlrev_b32_e32 v123, 16, v126
	v_add_f32_e32 v123, v116, v123
	v_and_b32_e32 v116, 0xffff0000, v126
	v_add_f32_e32 v124, v117, v116
	v_lshlrev_b32_e32 v116, 16, v127
	v_add_f32_e32 v125, v118, v116
	v_and_b32_e32 v116, 0xffff0000, v127
	v_add_f32_e32 v119, v119, v116
	v_mul_f32_e32 v116, v120, v120
	v_mul_f32_e32 v117, v122, v122
	v_fmac_f32_e32 v116, v0, v0
	v_fmac_f32_e32 v117, v121, v121
	v_add_f32_e32 v116, v116, v117
	v_mul_f32_e32 v117, v124, v124
	v_fmac_f32_e32 v117, v123, v123
	v_add_f32_e32 v116, v117, v116
	v_mul_f32_e32 v117, v119, v119
	v_fmac_f32_e32 v117, v125, v125
	v_add_f32_e32 v116, v117, v116
	v_add_f32_e32 v126, v159, v116
	v_cvt_pk_bf16_f32 v116, v0, v120
	v_cvt_pk_bf16_f32 v117, v121, v122
	v_cvt_pk_bf16_f32 v118, v123, v124
	v_cvt_pk_bf16_f32 v119, v125, v119
	global_store_dwordx4 v[2:3], v[116:119], off offset:256
	v_xor_b32_e32 v0, 16, v174
	s_nop 0
	v_and_b32_e32 v116, 64, v174
	v_add_u32_e32 v116, 64, v116
	v_cmp_lt_i32_e32 vcc, v0, v116
	s_nop 1
	v_cndmask_b32_e32 v0, v174, v0, vcc
	v_lshlrev_b32_e32 v0, 2, v0
	ds_bpermute_b32 v117, v0, v126
	s_waitcnt lgkmcnt(0)
	v_add_f32_e32 v118, v126, v117
	v_xor_b32_e32 v117, 32, v174
	v_cmp_lt_i32_e32 vcc, v117, v116
	s_nop 1
	v_cndmask_b32_e32 v116, v174, v117, vcc
	v_lshlrev_b32_e32 v120, 2, v116
	ds_bpermute_b32 v119, v120, v118
	v_lshl_add_u64 v[116:117], v[146:147], 2, s[58:59]
	s_and_saveexec_b64 s[42:43], s[4:5]
	s_cbranch_execz .LBB0_396
	s_waitcnt lgkmcnt(0)
	v_add_f32_e32 v118, v118, v119
	global_atomic_add_f32 v[116:117], v118, off
; __device__ __forceinline__ unsigned cvt_pk_bf16(float lo, float hi) { unsigned r; asm volatile("v_cvt_pk_bf16_f32 %0, %1, %2" : "=v"(r) : "v"(lo), "v"(hi)); return r; }
;     __device__ __forceinline__ void operator()(const f32x4 (&acc)[2][2][4][2], const Unit& u, int wr, int wc, int fr, int fq, int ui) const {
;     ...
;             for (int m = 0; m < 4; ++m) { const int r = row0 + ai * HALF + m * 16; bf16_t* xp = xb + (size_t)r * 1024 + col0; float ss = 0.f; const float sa = sc[(ui & 1) * 512 + 256 + ai * HALF + wr * 64 + m * 16 + fr];
; #pragma unroll
;                 for (int bj = 0; bj < 2; ++bj) {
;                     const u32x4 b = *(const u32x4*)(xp + bj * HALF);
;                     f32x4 v0 = acc[ai][bj][m][0] * sa, v1 = acc[ai][bj][m][1] * sa;
;                     v0[0] += __builtin_bit_cast(float, b.x << 16); v0[1] += __builtin_bit_cast(float, b.x & 0xffff0000u); v0[2] += __builtin_bit_cast(float, b.y << 16); v0[3] += __builtin_bit_cast(float, b.y & 0xffff0000u);
;                     v1[0] += __builtin_bit_cast(float, b.z << 16); v1[1] += __builtin_bit_cast(float, b.z & 0xffff0000u); v1[2] += __builtin_bit_cast(float, b.w << 16); v1[3] += __builtin_bit_cast(float, b.w & 0xffff0000u);
;                     ss += (v0[0] * v0[0] + v0[1] * v0[1]) + (v0[2] * v0[2] + v0[3] * v0[3]) + (v1[0] * v1[0] + v1[1] * v1[1]) + (v1[2] * v1[2] + v1[3] * v1[3]);
;                     u32x4 w; w.x = cvt_pk_bf16(v0[0], v0[1]); w.y = cvt_pk_bf16(v0[2], v0[3]); w.z = cvt_pk_bf16(v1[0], v1[1]); w.w = cvt_pk_bf16(v1[2], v1[3]);
;                     *(u32x4*)(xp + bj * HALF) = w; }
;                 ss += __shfl_xor(ss, 16); ss += __shfl_xor(ss, 32);
;                 if (fq == 0) unsafeAtomicAdd(rowss + r, ss);
.LBB0_396:
	s_or_b64 exec, exec, s[42:43]
	v_or_b32_e32 v118, 16, v146
	s_waitcnt lgkmcnt(0)
	v_ashrrev_i32_e32 v119, 31, v118
	v_lshlrev_b64 v[118:119], 11, v[118:119]
	v_lshl_add_u64 v[118:119], s[60:61], 0, v[118:119]
	v_lshl_add_u64 v[118:119], v[144:145], 1, v[118:119]
	s_nop 0
	ds_read_b32 v126, v157 offset:1088
	s_waitcnt lgkmcnt(0)
	v_pk_mul_f32 v[112:113], v[112:113], v[126:127] op_sel_hi:[1,0]
	v_pk_mul_f32 v[114:115], v[114:115], v[126:127] op_sel_hi:[1,0]
	v_pk_mul_f32 v[108:109], v[108:109], v[126:127] op_sel_hi:[1,0]
	v_pk_mul_f32 v[110:111], v[110:111], v[126:127] op_sel_hi:[1,0]
	v_pk_mul_f32 v[104:105], v[104:105], v[126:127] op_sel_hi:[1,0]
	v_pk_mul_f32 v[106:107], v[106:107], v[126:127] op_sel_hi:[1,0]
	v_pk_mul_f32 v[100:101], v[100:101], v[126:127] op_sel_hi:[1,0]
	v_pk_mul_f32 v[102:103], v[102:103], v[126:127] op_sel_hi:[1,0]
	s_waitcnt vmcnt(15)
	s_nop 1
	v_mov_b64_e32 v[122:123], v[178:179]
	v_mov_b64_e32 v[124:125], v[180:181]
	v_lshlrev_b32_e32 v121, 16, v122
	v_add_f32_e32 v112, v112, v121
	v_and_b32_e32 v121, 0xffff0000, v122
	v_add_f32_e32 v113, v113, v121
	v_lshlrev_b32_e32 v121, 16, v123
	v_add_f32_e32 v114, v114, v121
	v_and_b32_e32 v121, 0xffff0000, v123
	v_add_f32_e32 v115, v115, v121
	v_lshlrev_b32_e32 v121, 16, v124
	v_add_f32_e32 v121, v108, v121
	v_and_b32_e32 v108, 0xffff0000, v124
	v_add_f32_e32 v122, v109, v108
	v_lshlrev_b32_e32 v108, 16, v125
	v_add_f32_e32 v123, v110, v108
	v_and_b32_e32 v108, 0xffff0000, v125
	v_add_f32_e32 v111, v111, v108
	v_mul_f32_e32 v108, v113, v113
	v_mul_f32_e32 v109, v115, v115
	v_fmac_f32_e32 v108, v112, v112
	v_fmac_f32_e32 v109, v114, v114
	v_add_f32_e32 v108, v108, v109
	v_mul_f32_e32 v109, v122, v122
	v_fmac_f32_e32 v109, v121, v121
	v_add_f32_e32 v108, v109, v108
	v_mul_f32_e32 v109, v111, v111
	v_fmac_f32_e32 v109, v123, v123
	v_add_f32_e32 v124, v109, v108
	v_cvt_pk_bf16_f32 v108, v112, v113
	v_cvt_pk_bf16_f32 v109, v114, v115
	v_cvt_pk_bf16_f32 v110, v121, v122
	v_cvt_pk_bf16_f32 v111, v123, v111
	global_store_dwordx4 v[118:119], v[108:111], off
	s_nop 0
	s_waitcnt vmcnt(15)
	s_nop 1
	v_mov_b64_e32 v[108:109], v[182:183]
	v_mov_b64_e32 v[110:111], v[184:185]
	v_lshlrev_b32_e32 v112, 16, v108
	v_and_b32_e32 v108, 0xffff0000, v108
	v_add_f32_e32 v105, v105, v108
	v_lshlrev_b32_e32 v108, 16, v109
	v_add_f32_e32 v106, v106, v108
	v_and_b32_e32 v108, 0xffff0000, v109
	v_add_f32_e32 v107, v107, v108
	v_lshlrev_b32_e32 v108, 16, v110
	v_add_f32_e32 v108, v100, v108
	v_and_b32_e32 v100, 0xffff0000, v110
	v_add_f32_e32 v109, v101, v100
	v_lshlrev_b32_e32 v100, 16, v111
	v_add_f32_e32 v110, v102, v100
	v_and_b32_e32 v100, 0xffff0000, v111
	v_add_f32_e32 v104, v104, v112
	v_add_f32_e32 v103, v103, v100
	v_mul_f32_e32 v100, v105, v105
	v_mul_f32_e32 v101, v107, v107
	v_fmac_f32_e32 v100, v104, v104
	v_fmac_f32_e32 v101, v106, v106
	v_add_f32_e32 v100, v100, v101
	v_mul_f32_e32 v101, v109, v109
	v_fmac_f32_e32 v101, v108, v108
	v_add_f32_e32 v100, v101, v100
	v_mul_f32_e32 v101, v103, v103
	v_fmac_f32_e32 v101, v110, v110
	v_add_f32_e32 v100, v101, v100
	v_add_f32_e32 v111, v124, v100
	v_cvt_pk_bf16_f32 v100, v104, v105
	v_cvt_pk_bf16_f32 v101, v106, v107
	v_cvt_pk_bf16_f32 v102, v108, v109
	v_cvt_pk_bf16_f32 v103, v110, v103
	global_store_dwordx4 v[118:119], v[100:103], off offset:256
	ds_bpermute_b32 v100, v0, v111
	s_waitcnt lgkmcnt(0)
	v_add_f32_e32 v100, v111, v100
	ds_bpermute_b32 v101, v120, v100
	s_and_saveexec_b64 s[42:43], s[4:5]
	s_cbranch_execz .LBB0_398
	s_waitcnt lgkmcnt(0)
	v_add_f32_e32 v100, v100, v101
	global_atomic_add_f32 v[116:117], v100, off offset:64
.LBB0_398:
	s_or_b64 exec, exec, s[42:43]
	v_or_b32_e32 v100, 32, v146
	s_waitcnt lgkmcnt(0)
	v_ashrrev_i32_e32 v101, 31, v100
	v_lshlrev_b64 v[100:101], 11, v[100:101]
	v_lshl_add_u64 v[100:101], s[60:61], 0, v[100:101]
	v_lshl_add_u64 v[100:101], v[144:145], 1, v[100:101]
	s_nop 0
	ds_read_b32 v106, v157 offset:1152
	s_waitcnt lgkmcnt(0)
	v_pk_mul_f32 v[98:99], v[98:99], v[106:107] op_sel_hi:[1,0]
	v_pk_mul_f32 v[96:97], v[96:97], v[106:107] op_sel_hi:[1,0]
	v_pk_mul_f32 v[94:95], v[94:95], v[106:107] op_sel_hi:[1,0]
	v_pk_mul_f32 v[92:93], v[92:93], v[106:107] op_sel_hi:[1,0]
	s_waitcnt vmcnt(15)
	s_nop 1
	v_mov_b64_e32 v[102:103], v[186:187]
	v_mov_b64_e32 v[104:105], v[188:189]
	v_lshlrev_b32_e32 v107, 16, v102
	v_and_b32_e32 v102, 0xffff0000, v102
	v_add_f32_e32 v97, v97, v102
	v_lshlrev_b32_e32 v102, 16, v103
	v_add_f32_e32 v98, v98, v102
	v_and_b32_e32 v102, 0xffff0000, v103
	v_add_f32_e32 v99, v99, v102
	v_lshlrev_b32_e32 v102, 16, v104
	v_add_f32_e32 v102, v92, v102
	v_and_b32_e32 v92, 0xffff0000, v104
	v_add_f32_e32 v103, v93, v92
	v_lshlrev_b32_e32 v92, 16, v105
	v_add_f32_e32 v104, v94, v92
	v_and_b32_e32 v92, 0xffff0000, v105
	v_add_f32_e32 v96, v96, v107
	v_add_f32_e32 v95, v95, v92
	v_mul_f32_e32 v92, v97, v97
	v_mul_f32_e32 v93, v99, v99
	v_fmac_f32_e32 v92, v96, v96
	v_fmac_f32_e32 v93, v98, v98
	v_add_f32_e32 v92, v92, v93
	v_mul_f32_e32 v93, v103, v103
	v_fmac_f32_e32 v93, v102, v102
	v_add_f32_e32 v92, v93, v92
	v_mul_f32_e32 v93, v95, v95
	v_fmac_f32_e32 v93, v104, v104
	v_add_f32_e32 v105, v93, v92
	v_cvt_pk_bf16_f32 v92, v96, v97
	v_cvt_pk_bf16_f32 v93, v98, v99
	v_cvt_pk_bf16_f32 v94, v102, v103
	v_cvt_pk_bf16_f32 v95, v104, v95
	global_store_dwordx4 v[100:101], v[92:95], off
	s_nop 0
	v_pk_mul_f32 v[88:89], v[88:89], v[106:107] op_sel_hi:[1,0]
	v_pk_mul_f32 v[90:91], v[90:91], v[106:107] op_sel_hi:[1,0]
	v_pk_mul_f32 v[84:85], v[84:85], v[106:107] op_sel_hi:[1,0]
	v_pk_mul_f32 v[86:87], v[86:87], v[106:107] op_sel_hi:[1,0]
	s_waitcnt vmcnt(15)
	s_nop 1
	v_mov_b64_e32 v[92:93], v[190:191]
	v_mov_b64_e32 v[94:95], v[192:193]
	v_lshlrev_b32_e32 v96, 16, v92
	v_and_b32_e32 v92, 0xffff0000, v92
	v_add_f32_e32 v89, v89, v92
	v_lshlrev_b32_e32 v92, 16, v93
	v_add_f32_e32 v90, v90, v92
	v_and_b32_e32 v92, 0xffff0000, v93
	v_add_f32_e32 v91, v91, v92
	v_lshlrev_b32_e32 v92, 16, v94
	v_add_f32_e32 v92, v84, v92
	v_and_b32_e32 v84, 0xffff0000, v94
	v_add_f32_e32 v93, v85, v84
	v_lshlrev_b32_e32 v84, 16, v95
	v_add_f32_e32 v94, v86, v84
	v_and_b32_e32 v84, 0xffff0000, v95
	v_add_f32_e32 v88, v88, v96
	v_add_f32_e32 v87, v87, v84
	v_mul_f32_e32 v84, v89, v89
	v_mul_f32_e32 v85, v91, v91
	v_fmac_f32_e32 v84, v88, v88
	v_fmac_f32_e32 v85, v90, v90
	v_add_f32_e32 v84, v84, v85
	v_mul_f32_e32 v85, v93, v93
	v_fmac_f32_e32 v85, v92, v92
	v_add_f32_e32 v84, v85, v84
	v_mul_f32_e32 v85, v87, v87
	v_fmac_f32_e32 v85, v94, v94
	v_add_f32_e32 v84, v85, v84
	v_add_f32_e32 v95, v105, v84
	v_cvt_pk_bf16_f32 v84, v88, v89
	v_cvt_pk_bf16_f32 v85, v90, v91
	v_cvt_pk_bf16_f32 v86, v92, v93
	v_cvt_pk_bf16_f32 v87, v94, v87
	global_store_dwordx4 v[100:101], v[84:87], off offset:256
	ds_bpermute_b32 v84, v0, v95
	s_waitcnt lgkmcnt(0)
	v_add_f32_e32 v84, v95, v84
	ds_bpermute_b32 v85, v120, v84
	s_and_saveexec_b64 s[42:43], s[4:5]
	s_cbranch_execz .LBB0_400
	s_waitcnt lgkmcnt(0)
	v_add_f32_e32 v84, v84, v85
	global_atomic_add_f32 v[116:117], v84, off offset:128
; __device__ __forceinline__ unsigned cvt_pk_bf16(float lo, float hi) { unsigned r; asm volatile("v_cvt_pk_bf16_f32 %0, %1, %2" : "=v"(r) : "v"(lo), "v"(hi)); return r; }
;     __device__ __forceinline__ void operator()(const f32x4 (&acc)[2][2][4][2], const Unit& u, int wr, int wc, int fr, int fq, int ui) const {
;     ...
;             for (int m = 0; m < 4; ++m) { const int r = row0 + ai * HALF + m * 16; bf16_t* xp = xb + (size_t)r * 1024 + col0; float ss = 0.f; const float sa = sc[(ui & 1) * 512 + 256 + ai * HALF + wr * 64 + m * 16 + fr];
; #pragma unroll
;                 for (int bj = 0; bj < 2; ++bj) {
;                     const u32x4 b = *(const u32x4*)(xp + bj * HALF);
;                     f32x4 v0 = acc[ai][bj][m][0] * sa, v1 = acc[ai][bj][m][1] * sa;
;                     v0[0] += __builtin_bit_cast(float, b.x << 16); v0[1] += __builtin_bit_cast(float, b.x & 0xffff0000u); v0[2] += __builtin_bit_cast(float, b.y << 16); v0[3] += __builtin_bit_cast(float, b.y & 0xffff0000u);
;                     v1[0] += __builtin_bit_cast(float, b.z << 16); v1[1] += __builtin_bit_cast(float, b.z & 0xffff0000u); v1[2] += __builtin_bit_cast(float, b.w << 16); v1[3] += __builtin_bit_cast(float, b.w & 0xffff0000u);
;                     ss += (v0[0] * v0[0] + v0[1] * v0[1]) + (v0[2] * v0[2] + v0[3] * v0[3]) + (v1[0] * v1[0] + v1[1] * v1[1]) + (v1[2] * v1[2] + v1[3] * v1[3]);
;                     u32x4 w; w.x = cvt_pk_bf16(v0[0], v0[1]); w.y = cvt_pk_bf16(v0[2], v0[3]); w.z = cvt_pk_bf16(v1[0], v1[1]); w.w = cvt_pk_bf16(v1[2], v1[3]);
;                     *(u32x4*)(xp + bj * HALF) = w; }
;                 ss += __shfl_xor(ss, 16); ss += __shfl_xor(ss, 32);
;                 if (fq == 0) unsafeAtomicAdd(rowss + r, ss);
.LBB0_400:
	s_or_b64 exec, exec, s[42:43]
	v_or_b32_e32 v84, 48, v146
	s_waitcnt lgkmcnt(0)
	v_ashrrev_i32_e32 v85, 31, v84
	v_lshlrev_b64 v[84:85], 11, v[84:85]
	v_lshl_add_u64 v[84:85], s[60:61], 0, v[84:85]
	v_lshl_add_u64 v[84:85], v[144:145], 1, v[84:85]
	s_nop 0
	ds_read_b32 v90, v157 offset:1216
	s_waitcnt lgkmcnt(0)
	v_pk_mul_f32 v[82:83], v[82:83], v[90:91] op_sel_hi:[1,0]
	v_pk_mul_f32 v[80:81], v[80:81], v[90:91] op_sel_hi:[1,0]
	v_pk_mul_f32 v[78:79], v[78:79], v[90:91] op_sel_hi:[1,0]
	v_pk_mul_f32 v[76:77], v[76:77], v[90:91] op_sel_hi:[1,0]
	s_waitcnt vmcnt(15)
	s_nop 1
	v_mov_b64_e32 v[86:87], v[194:195]
	v_mov_b64_e32 v[88:89], v[196:197]
	v_lshlrev_b32_e32 v91, 16, v86
	v_and_b32_e32 v86, 0xffff0000, v86
	v_add_f32_e32 v81, v81, v86
	v_lshlrev_b32_e32 v86, 16, v87
	v_add_f32_e32 v82, v82, v86
	v_and_b32_e32 v86, 0xffff0000, v87
	v_add_f32_e32 v83, v83, v86
	v_lshlrev_b32_e32 v86, 16, v88
	v_add_f32_e32 v86, v76, v86
	v_and_b32_e32 v76, 0xffff0000, v88
	v_add_f32_e32 v87, v77, v76
	v_lshlrev_b32_e32 v76, 16, v89
	v_add_f32_e32 v88, v78, v76
	v_and_b32_e32 v76, 0xffff0000, v89
	v_add_f32_e32 v80, v80, v91
	v_add_f32_e32 v79, v79, v76
	v_mul_f32_e32 v76, v81, v81
	v_mul_f32_e32 v77, v83, v83
	v_fmac_f32_e32 v76, v80, v80
	v_fmac_f32_e32 v77, v82, v82
	v_add_f32_e32 v76, v76, v77
	v_mul_f32_e32 v77, v87, v87
	v_fmac_f32_e32 v77, v86, v86
	v_add_f32_e32 v76, v77, v76
	v_mul_f32_e32 v77, v79, v79
	v_fmac_f32_e32 v77, v88, v88
	v_add_f32_e32 v89, v77, v76
	v_cvt_pk_bf16_f32 v76, v80, v81
	v_cvt_pk_bf16_f32 v77, v82, v83
	v_cvt_pk_bf16_f32 v78, v86, v87
	v_cvt_pk_bf16_f32 v79, v88, v79
	global_store_dwordx4 v[84:85], v[76:79], off
	s_nop 0
	v_pk_mul_f32 v[72:73], v[72:73], v[90:91] op_sel_hi:[1,0]
	v_pk_mul_f32 v[74:75], v[74:75], v[90:91] op_sel_hi:[1,0]
	v_pk_mul_f32 v[68:69], v[68:69], v[90:91] op_sel_hi:[1,0]
	v_pk_mul_f32 v[70:71], v[70:71], v[90:91] op_sel_hi:[1,0]
	s_waitcnt vmcnt(15)
	s_nop 1
	v_mov_b64_e32 v[76:77], v[198:199]
	v_mov_b64_e32 v[78:79], v[200:201]
	v_lshlrev_b32_e32 v80, 16, v76
	v_and_b32_e32 v76, 0xffff0000, v76
	v_add_f32_e32 v73, v73, v76
	v_lshlrev_b32_e32 v76, 16, v77
	v_add_f32_e32 v74, v74, v76
	v_and_b32_e32 v76, 0xffff0000, v77
	v_add_f32_e32 v75, v75, v76
	v_lshlrev_b32_e32 v76, 16, v78
	v_add_f32_e32 v76, v68, v76
	v_and_b32_e32 v68, 0xffff0000, v78
	v_add_f32_e32 v77, v69, v68
	v_lshlrev_b32_e32 v68, 16, v79
	v_add_f32_e32 v78, v70, v68
	v_and_b32_e32 v68, 0xffff0000, v79
	v_add_f32_e32 v72, v72, v80
	v_add_f32_e32 v71, v71, v68
	v_mul_f32_e32 v68, v73, v73
	v_mul_f32_e32 v69, v75, v75
	v_fmac_f32_e32 v68, v72, v72
	v_fmac_f32_e32 v69, v74, v74
	v_add_f32_e32 v68, v68, v69
	v_mul_f32_e32 v69, v77, v77
	v_fmac_f32_e32 v69, v76, v76
	v_add_f32_e32 v68, v69, v68
	v_mul_f32_e32 v69, v71, v71
	v_fmac_f32_e32 v69, v78, v78
	v_add_f32_e32 v68, v69, v68
	v_add_f32_e32 v79, v89, v68
	v_cvt_pk_bf16_f32 v68, v72, v73
	v_cvt_pk_bf16_f32 v69, v74, v75
	v_cvt_pk_bf16_f32 v70, v76, v77
	v_cvt_pk_bf16_f32 v71, v78, v71
	global_store_dwordx4 v[84:85], v[68:71], off offset:256
	ds_bpermute_b32 v68, v0, v79
	s_waitcnt lgkmcnt(0)
	v_add_f32_e32 v68, v79, v68
	ds_bpermute_b32 v69, v120, v68
	s_and_saveexec_b64 s[42:43], s[4:5]
	s_cbranch_execz .LBB0_402
	s_waitcnt lgkmcnt(0)
	v_add_f32_e32 v68, v68, v69
	global_atomic_add_f32 v[116:117], v68, off offset:192
.LBB0_402:
	s_or_b64 exec, exec, s[42:43]
	v_add_co_u32_e32 v76, vcc, 0x40000, v2
	ds_read_b32 v74, v157 offset:1536
	s_nop 0
	v_addc_co_u32_e32 v77, vcc, 0, v3, vcc
	s_nop 0
	s_mov_b64 s[42:43], 0x40000
	s_waitcnt lgkmcnt(0)
	v_pk_mul_f32 v[66:67], v[66:67], v[74:75] op_sel_hi:[1,0]
	v_pk_mul_f32 v[64:65], v[64:65], v[74:75] op_sel_hi:[1,0]
	v_pk_mul_f32 v[62:63], v[62:63], v[74:75] op_sel_hi:[1,0]
	v_pk_mul_f32 v[60:61], v[60:61], v[74:75] op_sel_hi:[1,0]
	v_lshl_add_u64 v[68:69], v[2:3], 0, s[42:43]
	s_waitcnt vmcnt(15)
	s_nop 1
	v_mov_b64_e32 v[70:71], v[202:203]
	v_mov_b64_e32 v[72:73], v[204:205]
	v_lshlrev_b32_e32 v75, 16, v70
	v_and_b32_e32 v70, 0xffff0000, v70
	v_add_f32_e32 v65, v65, v70
	v_lshlrev_b32_e32 v70, 16, v71
	v_add_f32_e32 v66, v66, v70
	v_and_b32_e32 v70, 0xffff0000, v71
	v_add_f32_e32 v67, v67, v70
	v_lshlrev_b32_e32 v70, 16, v72
	v_add_f32_e32 v70, v60, v70
	v_and_b32_e32 v60, 0xffff0000, v72
	v_add_f32_e32 v71, v61, v60
	v_lshlrev_b32_e32 v60, 16, v73
	v_add_f32_e32 v72, v62, v60
	v_and_b32_e32 v60, 0xffff0000, v73
	v_add_f32_e32 v64, v64, v75
	v_add_f32_e32 v63, v63, v60
	v_mul_f32_e32 v60, v65, v65
	v_mul_f32_e32 v61, v67, v67
	v_fmac_f32_e32 v60, v64, v64
	v_fmac_f32_e32 v61, v66, v66
	v_add_f32_e32 v60, v60, v61
	v_mul_f32_e32 v61, v71, v71
	v_fmac_f32_e32 v61, v70, v70
	v_add_f32_e32 v60, v61, v60
	v_mul_f32_e32 v61, v63, v63
	v_fmac_f32_e32 v61, v72, v72
	v_add_f32_e32 v73, v61, v60
	v_cvt_pk_bf16_f32 v60, v64, v65
	v_cvt_pk_bf16_f32 v61, v66, v67
	v_cvt_pk_bf16_f32 v62, v70, v71
	v_cvt_pk_bf16_f32 v63, v72, v63
	global_store_dwordx4 v[76:77], v[60:63], off
	s_nop 0
	v_pk_mul_f32 v[56:57], v[56:57], v[74:75] op_sel_hi:[1,0]
	v_pk_mul_f32 v[58:59], v[58:59], v[74:75] op_sel_hi:[1,0]
	v_pk_mul_f32 v[52:53], v[52:53], v[74:75] op_sel_hi:[1,0]
	v_pk_mul_f32 v[54:55], v[54:55], v[74:75] op_sel_hi:[1,0]
	s_waitcnt vmcnt(15)
	s_nop 1
	v_mov_b64_e32 v[60:61], v[206:207]
	v_mov_b64_e32 v[62:63], v[208:209]
	v_lshlrev_b32_e32 v64, 16, v60
	v_and_b32_e32 v60, 0xffff0000, v60
	v_add_f32_e32 v57, v57, v60
	v_lshlrev_b32_e32 v60, 16, v61
	v_add_f32_e32 v58, v58, v60
	v_and_b32_e32 v60, 0xffff0000, v61
	v_add_f32_e32 v59, v59, v60
	v_lshlrev_b32_e32 v60, 16, v62
	v_add_f32_e32 v60, v52, v60
	v_and_b32_e32 v52, 0xffff0000, v62
	v_add_f32_e32 v61, v53, v52
	v_lshlrev_b32_e32 v52, 16, v63
	v_add_f32_e32 v62, v54, v52
	v_and_b32_e32 v52, 0xffff0000, v63
	v_add_f32_e32 v56, v56, v64
	v_add_f32_e32 v55, v55, v52
	v_mul_f32_e32 v52, v57, v57
	v_mul_f32_e32 v53, v59, v59
	v_fmac_f32_e32 v52, v56, v56
	v_fmac_f32_e32 v53, v58, v58
	v_add_f32_e32 v52, v52, v53
	v_mul_f32_e32 v53, v61, v61
	v_fmac_f32_e32 v53, v60, v60
	v_add_f32_e32 v52, v53, v52
	v_mul_f32_e32 v53, v55, v55
	v_fmac_f32_e32 v53, v62, v62
	v_add_f32_e32 v52, v53, v52
	v_add_f32_e32 v63, v73, v52
	v_cvt_pk_bf16_f32 v52, v56, v57
	v_cvt_pk_bf16_f32 v53, v58, v59
	v_cvt_pk_bf16_f32 v54, v60, v61
	v_cvt_pk_bf16_f32 v55, v62, v55
	global_store_dwordx4 v[68:69], v[52:55], off offset:256
	ds_bpermute_b32 v52, v0, v63
	s_waitcnt lgkmcnt(0)
	v_add_f32_e32 v52, v63, v52
	ds_bpermute_b32 v53, v120, v52
	s_and_saveexec_b64 s[42:43], s[4:5]
	s_cbranch_execz .LBB0_404
	s_waitcnt lgkmcnt(0)
	v_add_f32_e32 v52, v52, v53
	global_atomic_add_f32 v[116:117], v52, off offset:512
; __device__ __forceinline__ unsigned cvt_pk_bf16(float lo, float hi) { unsigned r; asm volatile("v_cvt_pk_bf16_f32 %0, %1, %2" : "=v"(r) : "v"(lo), "v"(hi)); return r; }
;     __device__ __forceinline__ void operator()(const f32x4 (&acc)[2][2][4][2], const Unit& u, int wr, int wc, int fr, int fq, int ui) const {
;     ...
;             for (int m = 0; m < 4; ++m) { const int r = row0 + ai * HALF + m * 16; bf16_t* xp = xb + (size_t)r * 1024 + col0; float ss = 0.f; const float sa = sc[(ui & 1) * 512 + 256 + ai * HALF + wr * 64 + m * 16 + fr];
; #pragma unroll
;                 for (int bj = 0; bj < 2; ++bj) {
;                     const u32x4 b = *(const u32x4*)(xp + bj * HALF);
;                     f32x4 v0 = acc[ai][bj][m][0] * sa, v1 = acc[ai][bj][m][1] * sa;
;                     v0[0] += __builtin_bit_cast(float, b.x << 16); v0[1] += __builtin_bit_cast(float, b.x & 0xffff0000u); v0[2] += __builtin_bit_cast(float, b.y << 16); v0[3] += __builtin_bit_cast(float, b.y & 0xffff0000u);
;                     v1[0] += __builtin_bit_cast(float, b.z << 16); v1[1] += __builtin_bit_cast(float, b.z & 0xffff0000u); v1[2] += __builtin_bit_cast(float, b.w << 16); v1[3] += __builtin_bit_cast(float, b.w & 0xffff0000u);
;                     ss += (v0[0] * v0[0] + v0[1] * v0[1]) + (v0[2] * v0[2] + v0[3] * v0[3]) + (v1[0] * v1[0] + v1[1] * v1[1]) + (v1[2] * v1[2] + v1[3] * v1[3]);
;                     u32x4 w; w.x = cvt_pk_bf16(v0[0], v0[1]); w.y = cvt_pk_bf16(v0[2], v0[3]); w.z = cvt_pk_bf16(v1[0], v1[1]); w.w = cvt_pk_bf16(v1[2], v1[3]);
;                     *(u32x4*)(xp + bj * HALF) = w; }
;                 ss += __shfl_xor(ss, 16); ss += __shfl_xor(ss, 32);
;                 if (fq == 0) unsafeAtomicAdd(rowss + r, ss);
.LBB0_404:
	s_or_b64 exec, exec, s[42:43]
	v_add_co_u32_e32 v60, vcc, 0x48000, v2
	ds_read_b32 v58, v157 offset:1600
	s_nop 0
	v_addc_co_u32_e32 v61, vcc, 0, v3, vcc
	s_nop 0
	s_mov_b64 s[42:43], 0x48000
	s_waitcnt lgkmcnt(0)
	v_pk_mul_f32 v[50:51], v[50:51], v[58:59] op_sel_hi:[1,0]
	v_pk_mul_f32 v[48:49], v[48:49], v[58:59] op_sel_hi:[1,0]
	v_pk_mul_f32 v[46:47], v[46:47], v[58:59] op_sel_hi:[1,0]
	v_pk_mul_f32 v[44:45], v[44:45], v[58:59] op_sel_hi:[1,0]
	v_lshl_add_u64 v[52:53], v[2:3], 0, s[42:43]
	s_waitcnt vmcnt(15)
	s_nop 1
	v_mov_b64_e32 v[54:55], v[210:211]
	v_mov_b64_e32 v[56:57], v[212:213]
	v_lshlrev_b32_e32 v59, 16, v54
	v_and_b32_e32 v54, 0xffff0000, v54
	v_add_f32_e32 v49, v49, v54
	v_lshlrev_b32_e32 v54, 16, v55
	v_add_f32_e32 v50, v50, v54
	v_and_b32_e32 v54, 0xffff0000, v55
	v_add_f32_e32 v51, v51, v54
	v_lshlrev_b32_e32 v54, 16, v56
	v_add_f32_e32 v54, v44, v54
	v_and_b32_e32 v44, 0xffff0000, v56
	v_add_f32_e32 v55, v45, v44
	v_lshlrev_b32_e32 v44, 16, v57
	v_add_f32_e32 v56, v46, v44
	v_and_b32_e32 v44, 0xffff0000, v57
	v_add_f32_e32 v48, v48, v59
	v_add_f32_e32 v47, v47, v44
	v_mul_f32_e32 v44, v49, v49
	v_mul_f32_e32 v45, v51, v51
	v_fmac_f32_e32 v44, v48, v48
	v_fmac_f32_e32 v45, v50, v50
	v_add_f32_e32 v44, v44, v45
	v_mul_f32_e32 v45, v55, v55
	v_fmac_f32_e32 v45, v54, v54
	v_add_f32_e32 v44, v45, v44
	v_mul_f32_e32 v45, v47, v47
	v_fmac_f32_e32 v45, v56, v56
	v_add_f32_e32 v57, v45, v44
	v_cvt_pk_bf16_f32 v44, v48, v49
	v_cvt_pk_bf16_f32 v45, v50, v51
	v_cvt_pk_bf16_f32 v46, v54, v55
	v_cvt_pk_bf16_f32 v47, v56, v47
	global_store_dwordx4 v[60:61], v[44:47], off
	s_nop 0
	v_pk_mul_f32 v[40:41], v[40:41], v[58:59] op_sel_hi:[1,0]
	v_pk_mul_f32 v[42:43], v[42:43], v[58:59] op_sel_hi:[1,0]
	v_pk_mul_f32 v[36:37], v[36:37], v[58:59] op_sel_hi:[1,0]
	v_pk_mul_f32 v[38:39], v[38:39], v[58:59] op_sel_hi:[1,0]
	s_waitcnt vmcnt(15)
	s_nop 1
	v_mov_b64_e32 v[44:45], v[214:215]
	v_mov_b64_e32 v[46:47], v[216:217]
	v_lshlrev_b32_e32 v48, 16, v44
	v_and_b32_e32 v44, 0xffff0000, v44
	v_add_f32_e32 v41, v41, v44
	v_lshlrev_b32_e32 v44, 16, v45
	v_add_f32_e32 v42, v42, v44
	v_and_b32_e32 v44, 0xffff0000, v45
	v_add_f32_e32 v43, v43, v44
	v_lshlrev_b32_e32 v44, 16, v46
	v_add_f32_e32 v44, v36, v44
	v_and_b32_e32 v36, 0xffff0000, v46
	v_add_f32_e32 v45, v37, v36
	v_lshlrev_b32_e32 v36, 16, v47
	v_add_f32_e32 v46, v38, v36
	v_and_b32_e32 v36, 0xffff0000, v47
	v_add_f32_e32 v40, v40, v48
	v_add_f32_e32 v39, v39, v36
	v_mul_f32_e32 v36, v41, v41
	v_mul_f32_e32 v37, v43, v43
	v_fmac_f32_e32 v36, v40, v40
	v_fmac_f32_e32 v37, v42, v42
	v_add_f32_e32 v36, v36, v37
	v_mul_f32_e32 v37, v45, v45
	v_fmac_f32_e32 v37, v44, v44
	v_add_f32_e32 v36, v37, v36
	v_mul_f32_e32 v37, v39, v39
	v_fmac_f32_e32 v37, v46, v46
	v_add_f32_e32 v36, v37, v36
	v_add_f32_e32 v47, v57, v36
	v_cvt_pk_bf16_f32 v36, v40, v41
	v_cvt_pk_bf16_f32 v37, v42, v43
	v_cvt_pk_bf16_f32 v38, v44, v45
	v_cvt_pk_bf16_f32 v39, v46, v39
	global_store_dwordx4 v[52:53], v[36:39], off offset:256
	ds_bpermute_b32 v36, v0, v47
	s_waitcnt lgkmcnt(0)
	v_add_f32_e32 v36, v47, v36
	ds_bpermute_b32 v37, v120, v36
	s_and_saveexec_b64 s[42:43], s[4:5]
	s_cbranch_execz .LBB0_406
	s_waitcnt lgkmcnt(0)
	v_add_f32_e32 v36, v36, v37
	global_atomic_add_f32 v[116:117], v36, off offset:576
; __device__ __forceinline__ unsigned cvt_pk_bf16(float lo, float hi) { unsigned r; asm volatile("v_cvt_pk_bf16_f32 %0, %1, %2" : "=v"(r) : "v"(lo), "v"(hi)); return r; }
;     __device__ __forceinline__ void operator()(const f32x4 (&acc)[2][2][4][2], const Unit& u, int wr, int wc, int fr, int fq, int ui) const {
;     ...
;             for (int m = 0; m < 4; ++m) { const int r = row0 + ai * HALF + m * 16; bf16_t* xp = xb + (size_t)r * 1024 + col0; float ss = 0.f; const float sa = sc[(ui & 1) * 512 + 256 + ai * HALF + wr * 64 + m * 16 + fr];
; #pragma unroll
;                 for (int bj = 0; bj < 2; ++bj) {
;                     const u32x4 b = *(const u32x4*)(xp + bj * HALF);
;                     f32x4 v0 = acc[ai][bj][m][0] * sa, v1 = acc[ai][bj][m][1] * sa;
;                     v0[0] += __builtin_bit_cast(float, b.x << 16); v0[1] += __builtin_bit_cast(float, b.x & 0xffff0000u); v0[2] += __builtin_bit_cast(float, b.y << 16); v0[3] += __builtin_bit_cast(float, b.y & 0xffff0000u);
;                     v1[0] += __builtin_bit_cast(float, b.z << 16); v1[1] += __builtin_bit_cast(float, b.z & 0xffff0000u); v1[2] += __builtin_bit_cast(float, b.w << 16); v1[3] += __builtin_bit_cast(float, b.w & 0xffff0000u);
;                     ss += (v0[0] * v0[0] + v0[1] * v0[1]) + (v0[2] * v0[2] + v0[3] * v0[3]) + (v1[0] * v1[0] + v1[1] * v1[1]) + (v1[2] * v1[2] + v1[3] * v1[3]);
;                     u32x4 w; w.x = cvt_pk_bf16(v0[0], v0[1]); w.y = cvt_pk_bf16(v0[2], v0[3]); w.z = cvt_pk_bf16(v1[0], v1[1]); w.w = cvt_pk_bf16(v1[2], v1[3]);
;                     *(u32x4*)(xp + bj * HALF) = w; }
;                 ss += __shfl_xor(ss, 16); ss += __shfl_xor(ss, 32);
;                 if (fq == 0) unsafeAtomicAdd(rowss + r, ss);
.LBB0_406:
	s_or_b64 exec, exec, s[42:43]
	v_add_co_u32_e32 v44, vcc, 0x50000, v2
	ds_read_b32 v42, v157 offset:1664
	s_nop 0
	v_addc_co_u32_e32 v45, vcc, 0, v3, vcc
	s_nop 0
	s_mov_b64 s[42:43], 0x50000
	s_waitcnt lgkmcnt(0)
	v_pk_mul_f32 v[34:35], v[34:35], v[42:43] op_sel_hi:[1,0]
	v_pk_mul_f32 v[32:33], v[32:33], v[42:43] op_sel_hi:[1,0]
	v_pk_mul_f32 v[30:31], v[30:31], v[42:43] op_sel_hi:[1,0]
	v_pk_mul_f32 v[28:29], v[28:29], v[42:43] op_sel_hi:[1,0]
	v_lshl_add_u64 v[36:37], v[2:3], 0, s[42:43]
	s_waitcnt vmcnt(15)
	s_nop 1
	v_mov_b64_e32 v[38:39], v[218:219]
	v_mov_b64_e32 v[40:41], v[220:221]
	v_lshlrev_b32_e32 v43, 16, v38
	v_and_b32_e32 v38, 0xffff0000, v38
	v_add_f32_e32 v33, v33, v38
	v_lshlrev_b32_e32 v38, 16, v39
	v_add_f32_e32 v34, v34, v38
	v_and_b32_e32 v38, 0xffff0000, v39
	v_add_f32_e32 v35, v35, v38
	v_lshlrev_b32_e32 v38, 16, v40
	v_add_f32_e32 v38, v28, v38
	v_and_b32_e32 v28, 0xffff0000, v40
	v_add_f32_e32 v39, v29, v28
	v_lshlrev_b32_e32 v28, 16, v41
	v_add_f32_e32 v40, v30, v28
	v_and_b32_e32 v28, 0xffff0000, v41
	v_add_f32_e32 v32, v32, v43
	v_add_f32_e32 v31, v31, v28
	v_mul_f32_e32 v28, v33, v33
	v_mul_f32_e32 v29, v35, v35
	v_fmac_f32_e32 v28, v32, v32
	v_fmac_f32_e32 v29, v34, v34
	v_add_f32_e32 v28, v28, v29
	v_mul_f32_e32 v29, v39, v39
	v_fmac_f32_e32 v29, v38, v38
	v_add_f32_e32 v28, v29, v28
	v_mul_f32_e32 v29, v31, v31
	v_fmac_f32_e32 v29, v40, v40
	v_add_f32_e32 v41, v29, v28
	v_cvt_pk_bf16_f32 v28, v32, v33
	v_cvt_pk_bf16_f32 v29, v34, v35
	v_cvt_pk_bf16_f32 v30, v38, v39
	v_cvt_pk_bf16_f32 v31, v40, v31
	global_store_dwordx4 v[44:45], v[28:31], off
	s_nop 0
	v_pk_mul_f32 v[24:25], v[24:25], v[42:43] op_sel_hi:[1,0]
	v_pk_mul_f32 v[26:27], v[26:27], v[42:43] op_sel_hi:[1,0]
	v_pk_mul_f32 v[20:21], v[20:21], v[42:43] op_sel_hi:[1,0]
	v_pk_mul_f32 v[22:23], v[22:23], v[42:43] op_sel_hi:[1,0]
	s_waitcnt vmcnt(15)
	s_nop 1
	v_mov_b64_e32 v[28:29], v[222:223]
	v_mov_b64_e32 v[30:31], v[224:225]
	v_lshlrev_b32_e32 v32, 16, v28
	v_and_b32_e32 v28, 0xffff0000, v28
	v_add_f32_e32 v25, v25, v28
	v_lshlrev_b32_e32 v28, 16, v29
	v_add_f32_e32 v26, v26, v28
	v_and_b32_e32 v28, 0xffff0000, v29
	v_add_f32_e32 v27, v27, v28
	v_lshlrev_b32_e32 v28, 16, v30
	v_add_f32_e32 v28, v20, v28
	v_and_b32_e32 v20, 0xffff0000, v30
	v_add_f32_e32 v29, v21, v20
	v_lshlrev_b32_e32 v20, 16, v31
	v_add_f32_e32 v30, v22, v20
	v_and_b32_e32 v20, 0xffff0000, v31
	v_add_f32_e32 v24, v24, v32
	v_add_f32_e32 v23, v23, v20
	v_mul_f32_e32 v20, v25, v25
	v_mul_f32_e32 v21, v27, v27
	v_fmac_f32_e32 v20, v24, v24
	v_fmac_f32_e32 v21, v26, v26
	v_add_f32_e32 v20, v20, v21
	v_mul_f32_e32 v21, v29, v29
	v_fmac_f32_e32 v21, v28, v28
	v_add_f32_e32 v20, v21, v20
	v_mul_f32_e32 v21, v23, v23
	v_fmac_f32_e32 v21, v30, v30
	v_add_f32_e32 v20, v21, v20
	v_add_f32_e32 v31, v41, v20
	v_cvt_pk_bf16_f32 v20, v24, v25
	v_cvt_pk_bf16_f32 v21, v26, v27
	v_cvt_pk_bf16_f32 v22, v28, v29
	v_cvt_pk_bf16_f32 v23, v30, v23
	global_store_dwordx4 v[36:37], v[20:23], off offset:256
	ds_bpermute_b32 v20, v0, v31
	s_waitcnt lgkmcnt(0)
	v_add_f32_e32 v20, v31, v20
	ds_bpermute_b32 v21, v120, v20
	s_and_saveexec_b64 s[42:43], s[4:5]
	s_cbranch_execz .LBB0_408
	s_waitcnt lgkmcnt(0)
	v_add_f32_e32 v20, v20, v21
	global_atomic_add_f32 v[116:117], v20, off offset:640
.LBB0_408:
	s_or_b64 exec, exec, s[42:43]
	s_mov_b64 s[42:43], 0x58000
	s_waitcnt lgkmcnt(0)
	v_lshl_add_u64 v[20:21], v[2:3], 0, s[42:43]
	v_add_co_u32_e32 v2, vcc, 0x58000, v2
	ds_read_b32 v26, v157 offset:1728
	s_nop 0
	v_addc_co_u32_e32 v3, vcc, 0, v3, vcc
	s_nop 0
	s_waitcnt lgkmcnt(0)
	v_pk_mul_f32 v[18:19], v[18:19], v[26:27] op_sel_hi:[1,0]
	v_pk_mul_f32 v[16:17], v[16:17], v[26:27] op_sel_hi:[1,0]
	v_pk_mul_f32 v[14:15], v[14:15], v[26:27] op_sel_hi:[1,0]
	v_pk_mul_f32 v[12:13], v[12:13], v[26:27] op_sel_hi:[1,0]
	s_waitcnt vmcnt(15)
	s_nop 1
	v_mov_b64_e32 v[22:23], v[226:227]
	v_mov_b64_e32 v[24:25], v[228:229]
	v_lshlrev_b32_e32 v27, 16, v22
	v_and_b32_e32 v22, 0xffff0000, v22
	v_add_f32_e32 v17, v17, v22
	v_lshlrev_b32_e32 v22, 16, v23
	v_add_f32_e32 v18, v18, v22
	v_and_b32_e32 v22, 0xffff0000, v23
	v_add_f32_e32 v19, v19, v22
	v_lshlrev_b32_e32 v22, 16, v24
	v_add_f32_e32 v22, v12, v22
	v_and_b32_e32 v12, 0xffff0000, v24
	v_add_f32_e32 v23, v13, v12
	v_lshlrev_b32_e32 v12, 16, v25
	v_add_f32_e32 v24, v14, v12
	v_and_b32_e32 v12, 0xffff0000, v25
	v_add_f32_e32 v16, v16, v27
	v_add_f32_e32 v15, v15, v12
	v_mul_f32_e32 v12, v17, v17
	v_mul_f32_e32 v13, v19, v19
	v_fmac_f32_e32 v12, v16, v16
	v_fmac_f32_e32 v13, v18, v18
	v_add_f32_e32 v12, v12, v13
	v_mul_f32_e32 v13, v23, v23
	v_fmac_f32_e32 v13, v22, v22
	v_add_f32_e32 v12, v13, v12
	v_mul_f32_e32 v13, v15, v15
	v_fmac_f32_e32 v13, v24, v24
	v_add_f32_e32 v25, v13, v12
	v_cvt_pk_bf16_f32 v12, v16, v17
	v_cvt_pk_bf16_f32 v13, v18, v19
	v_cvt_pk_bf16_f32 v14, v22, v23
	v_cvt_pk_bf16_f32 v15, v24, v15
	global_store_dwordx4 v[2:3], v[12:15], off
	s_nop 0
	v_pk_mul_f32 v[2:3], v[10:11], v[26:27] op_sel_hi:[1,0]
	v_pk_mul_f32 v[8:9], v[8:9], v[26:27] op_sel_hi:[1,0]
	v_pk_mul_f32 v[4:5], v[4:5], v[26:27] op_sel_hi:[1,0]
	v_pk_mul_f32 v[6:7], v[6:7], v[26:27] op_sel_hi:[1,0]
	s_waitcnt vmcnt(15)
	s_nop 1
	v_mov_b64_e32 v[12:13], v[230:231]
	v_mov_b64_e32 v[14:15], v[232:233]
	v_lshlrev_b32_e32 v10, 16, v12
	v_add_f32_e32 v8, v8, v10
	v_and_b32_e32 v10, 0xffff0000, v12
	v_add_f32_e32 v9, v9, v10
	v_lshlrev_b32_e32 v10, 16, v13
	v_add_f32_e32 v10, v2, v10
	v_and_b32_e32 v2, 0xffff0000, v13
	v_add_f32_e32 v3, v3, v2
	v_lshlrev_b32_e32 v2, 16, v14
	v_add_f32_e32 v4, v4, v2
	v_and_b32_e32 v2, 0xffff0000, v14
	v_add_f32_e32 v5, v5, v2
	v_lshlrev_b32_e32 v2, 16, v15
	v_add_f32_e32 v6, v6, v2
	v_and_b32_e32 v2, 0xffff0000, v15
	v_add_f32_e32 v7, v7, v2
	v_mul_f32_e32 v2, v9, v9
	v_mul_f32_e32 v11, v3, v3
	v_fmac_f32_e32 v2, v8, v8
	v_fmac_f32_e32 v11, v10, v10
	v_add_f32_e32 v2, v2, v11
	v_mul_f32_e32 v11, v5, v5
	v_fmac_f32_e32 v11, v4, v4
	v_add_f32_e32 v2, v11, v2
	v_mul_f32_e32 v11, v7, v7
	v_fmac_f32_e32 v11, v6, v6
	v_add_f32_e32 v2, v11, v2
	v_add_f32_e32 v11, v25, v2
	ds_bpermute_b32 v0, v0, v11
	v_cvt_pk_bf16_f32 v2, v8, v9
	v_cvt_pk_bf16_f32 v3, v10, v3
	v_cvt_pk_bf16_f32 v4, v4, v5
	v_cvt_pk_bf16_f32 v5, v6, v7
	s_waitcnt lgkmcnt(0)
	v_add_f32_e32 v0, v11, v0
	global_store_dwordx4 v[20:21], v[2:5], off offset:256
	ds_bpermute_b32 v2, v120, v0
	s_and_saveexec_b64 s[42:43], s[4:5]
	s_cbranch_execz .LBB0_410
	s_waitcnt lgkmcnt(0)
	v_add_f32_e32 v0, v0, v2
	global_atomic_add_f32 v[116:117], v0, off offset:704

; __device__ __forceinline__ unsigned xb_xcc_id() { return (unsigned)__builtin_amdgcn_s_getreg((3 << 11) | 20) & 0xFu; }
; __device__ __forceinline__ void xcd_barrier(const XcdBarrier& b) {
;     asm volatile("s_waitcnt vmcnt(0)" ::: "memory");
;     __syncthreads();
;     if (threadIdx.x == 0) {
;         unsigned* bar = b.bar;
;         __builtin_amdgcn_s_waitcnt(0);
; __global__ void __launch_bounds__(NWAVES * 64) fwd_kernel(Args a_) {
;     ...
;         if (ph + 1 < ph_hi) { XcdBarrier bar; bar.bar = (unsigned*)(ws + WS_BAR); bar.x = xb_xcc_id(); bar.st = MISC + 8; xcd_barrier(bar); }
.LBB0_431:
	s_add_i32 s18, s18, 1
	s_cmp_ge_i32 s18, s19
	s_mov_b64 s[4:5], -1
	s_cbranch_scc1 .LBB0_155
	s_cmp_eq_u32 s18, 3
	s_cbranch_scc1 .Lph_nobar
	s_cmp_eq_u32 s18, 8
	s_cbranch_scc1 .Lph_nobar
	s_cmp_eq_u32 s18, 13
	s_cbranch_scc1 .Lph_nobar
	s_cmp_eq_u32 s18, 18
	s_cbranch_scc1 .Lph_nobar
	s_branch .Lph_bar
.Lph_nobar:
	s_waitcnt vmcnt(0) lgkmcnt(0)
	s_barrier
	s_branch .LBB0_156
.Lph_bar:
	s_waitcnt lgkmcnt(0)
	s_getreg_b32 s0, hwreg(HW_REG_XCC_ID, 0, 4)
	s_waitcnt vmcnt(0)
	s_waitcnt vmcnt(0)
	s_barrier
	s_mov_b64 s[4:5], exec
	v_readlane_b32 s6, v255, 6
	v_readlane_b32 s7, v255, 7
	s_and_b64 s[6:7], s[4:5], s[6:7]
	s_mov_b64 exec, s[6:7]
	s_cbranch_execz .LBB0_154
	v_readlane_b32 s6, v255, 23
	s_waitcnt vmcnt(0) expcnt(0) lgkmcnt(0)
	s_and_b32 s0, s0, 15
	v_mov_b32_e32 v0, s6
	ds_read_b32 v3, v0
	v_readlane_b32 s6, v255, 24
	s_waitcnt lgkmcnt(0)
	v_cmp_ne_u32_e32 vcc, 0, v3
	v_mov_b32_e32 v0, s6
	ds_read_b32 v0, v0
	s_cbranch_vccnz .LBB0_448
	s_load_dwordx2 s[10:11], s[92:93], 0x0
	s_load_dword s9, s[92:93], 0x8
	s_add_u32 s6, s54, 0x1000
	s_addc_u32 s7, s55, 0
	s_add_u32 s8, s54, 0x1100
	s_waitcnt lgkmcnt(0)
	s_mul_i32 s16, s11, s10
	s_mul_i32 s16, s16, s9
	s_addc_u32 s9, s55, 0
	s_add_u32 s10, s54, 0x1200
	s_addc_u32 s11, s55, 0
	s_add_u32 s12, s54, 0x1300
	s_addc_u32 s13, s55, 0
	s_mov_b32 s17, 1
	s_branch .LBB0_436

; __global__ void __launch_bounds__(NWAVES * 64) fwd_kernel(Args a_) {
;     extern __shared__ __attribute__((aligned(16))) unsigned char lds_raw[];
	.amdhsa_kernel _Z10fwd_kernel4Args
		.amdhsa_group_segment_fixed_size 0
		.amdhsa_private_segment_fixed_size 0
		.amdhsa_kernarg_size 392
		.amdhsa_user_sgpr_count 2
		.amdhsa_user_sgpr_dispatch_ptr 0
		.amdhsa_user_sgpr_queue_ptr 0
		.amdhsa_user_sgpr_kernarg_segment_ptr 1
		.amdhsa_user_sgpr_dispatch_id 0
		.amdhsa_user_sgpr_kernarg_preload_length 0
		.amdhsa_user_sgpr_kernarg_preload_offset 0
		.amdhsa_user_sgpr_private_segment_size 0
		.amdhsa_uses_dynamic_stack 0
		.amdhsa_enable_private_segment 0
		.amdhsa_system_sgpr_workgroup_id_x 1
		.amdhsa_system_sgpr_workgroup_id_y 0
		.amdhsa_system_sgpr_workgroup_id_z 0
		.amdhsa_system_sgpr_workgroup_info 0
		.amdhsa_system_vgpr_workitem_id 2
		.amdhsa_next_free_vgpr 256
		.amdhsa_next_free_sgpr 102
		.amdhsa_accum_offset 256
		.amdhsa_reserve_vcc 1
		.amdhsa_float_round_mode_32 0
		.amdhsa_float_round_mode_16_64 0
		.amdhsa_float_denorm_mode_32 3
		.amdhsa_float_denorm_mode_16_64 3
		.amdhsa_dx10_clamp 1
		.amdhsa_ieee_mode 1
		.amdhsa_fp16_overflow 0
		.amdhsa_tg_split 0
		.amdhsa_exception_fp_ieee_invalid_op 0
		.amdhsa_exception_fp_denorm_src 0
		.amdhsa_exception_fp_ieee_div_zero 0
		.amdhsa_exception_fp_ieee_overflow 0
		.amdhsa_exception_fp_ieee_underflow 0
		.amdhsa_exception_fp_ieee_inexact 0
		.amdhsa_exception_int_div_zero 0
	.end_amdhsa_kernel

; __global__ void __launch_bounds__(NWAVES * 64) fwd_kernel(Args a_) {
;     extern __shared__ __attribute__((aligned(16))) unsigned char lds_raw[];
amdhsa.kernels:
  - .agpr_count:     0
    .args:
      - .offset:         0
        .size:           136
        .value_kind:     by_value
      - .offset:         136
        .size:           4
        .value_kind:     hidden_block_count_x
      - .offset:         140
        .size:           4
        .value_kind:     hidden_block_count_y
      - .offset:         144
        .size:           4
        .value_kind:     hidden_block_count_z
      - .offset:         148
        .size:           2
        .value_kind:     hidden_group_size_x
      - .offset:         150
        .size:           2
        .value_kind:     hidden_group_size_y
      - .offset:         152
        .size:           2
        .value_kind:     hidden_group_size_z
      - .offset:         154
        .size:           2
        .value_kind:     hidden_remainder_x
      - .offset:         156
        .size:           2
        .value_kind:     hidden_remainder_y
      - .offset:         158
        .size:           2
        .value_kind:     hidden_remainder_z
      - .offset:         176
        .size:           8
        .value_kind:     hidden_global_offset_x
      - .offset:         184
        .size:           8
        .value_kind:     hidden_global_offset_y
      - .offset:         192
        .size:           8
        .value_kind:     hidden_global_offset_z
      - .offset:         200
        .size:           2
        .value_kind:     hidden_grid_dims
      - .offset:         224
        .size:           8
        .value_kind:     hidden_multigrid_sync_arg
      - .offset:         256
        .size:           4
        .value_kind:     hidden_dynamic_lds_size
    .group_segment_fixed_size: 0
    .kernarg_segment_align: 8
    .kernarg_segment_size: 392
    .language:       OpenCL C
    .language_version:
      - 2
      - 0
    .max_flat_workgroup_size: 512
    .name:           _Z10fwd_kernel4Args
    .private_segment_fixed_size: 0
    .sgpr_count:     108
    .sgpr_spill_count: 51
    .symbol:         _Z10fwd_kernel4Args.kd
    .uniform_work_group_size: 1
    .uses_dynamic_stack: false
    .vgpr_count:     256
    .vgpr_spill_count: 0
    .wavefront_size: 64
